# removed all s_setprio flips from the 8-wave GEMM K-loops (48 MFMA blocks)
# baseline (speedup 1.0000x reference)
.LBB0_101:
	ds_read_b128 v[154:157], v151
	ds_read_b128 v[158:161], v151 offset:1024
	ds_read_b128 v[162:165], v151 offset:2048
	ds_read_b128 v[166:169], v151 offset:3072
	ds_read_b128 v[170:173], v152
	ds_read_b128 v[174:177], v152 offset:1024
	ds_read_b128 v[188:191], v152 offset:2048
	ds_read_b128 v[192:195], v152 offset:3072
	s_add_u32 s40, s36, s38
	s_addc_u32 s41, s37, s39
	s_add_u32 s44, s40, 0x100
	s_addc_u32 s45, s41, 0
	s_add_u32 s42, s66, s38
	s_addc_u32 s43, s67, s39
	s_add_u32 s40, s40, 0x180
	s_addc_u32 s41, s41, 0
	s_cmpk_eq_i32 s38, 0x1f00
	s_cselect_b32 s41, s65, s41
	s_cselect_b32 s40, s64, s40
	s_cselect_b32 s43, s35, s43
	s_cselect_b32 s42, s34, s42
	s_cselect_b32 s45, s23, s45
	s_cselect_b32 s44, s22, s44
	s_mov_b32 m0, s57
	v_lshl_add_u64 v[178:179], v[146:147], 0, s[38:39]
	ds_read_b128 v[196:199], v153
	ds_read_b128 v[200:203], v153 offset:1024
	ds_read_b128 v[204:207], v153 offset:2048
	ds_read_b128 v[208:211], v153 offset:3072
	ds_read_b128 v[214:217], v153 offset:4096
	ds_read_b128 v[218:221], v153 offset:5120
	ds_read_b128 v[222:225], v153 offset:6144
	ds_read_b128 v[226:229], v153 offset:7168
	global_load_lds_dwordx4 v[178:179], off
	v_lshl_add_u64 v[178:179], v[148:149], 0, s[38:39]
	s_add_i32 m0, s47, 0xe000
	s_nop 0
	global_load_lds_dwordx4 v[178:179], off
	s_waitcnt vmcnt(8)
	s_waitcnt lgkmcnt(0)
	s_barrier
	s_waitcnt lgkmcnt(0)
	v_mfma_f32_16x16x32_bf16 v[126:129], v[154:157], v[196:199], v[126:129]
	v_mfma_f32_16x16x32_bf16 v[122:125], v[162:165], v[196:199], v[122:125]
	v_mfma_f32_16x16x32_bf16 v[118:121], v[154:157], v[204:207], v[118:121]
	v_mfma_f32_16x16x32_bf16 v[110:113], v[162:165], v[204:207], v[110:113]
	v_mfma_f32_16x16x32_bf16 v[102:105], v[154:157], v[214:217], v[102:105]
	v_mfma_f32_16x16x32_bf16 v[94:97], v[162:165], v[214:217], v[94:97]
	v_mfma_f32_16x16x32_bf16 v[86:89], v[154:157], v[222:225], v[86:89]
	v_mfma_f32_16x16x32_bf16 v[78:81], v[162:165], v[222:225], v[78:81]
	v_mfma_f32_16x16x32_bf16 v[126:129], v[158:161], v[200:203], v[126:129]
	v_mfma_f32_16x16x32_bf16 v[122:125], v[166:169], v[200:203], v[122:125]
	v_mfma_f32_16x16x32_bf16 v[118:121], v[158:161], v[208:211], v[118:121]
	v_mfma_f32_16x16x32_bf16 v[110:113], v[166:169], v[208:211], v[110:113]
	v_mfma_f32_16x16x32_bf16 v[102:105], v[158:161], v[218:221], v[102:105]
	v_mfma_f32_16x16x32_bf16 v[94:97], v[166:169], v[218:221], v[94:97]
	v_mfma_f32_16x16x32_bf16 v[86:89], v[158:161], v[226:229], v[86:89]
	v_mfma_f32_16x16x32_bf16 v[78:81], v[166:169], v[226:229], v[78:81]
	v_mfma_f32_16x16x32_bf16 v[114:117], v[170:173], v[196:199], v[114:117]
	v_mfma_f32_16x16x32_bf16 v[106:109], v[188:191], v[196:199], v[106:109]
	v_mfma_f32_16x16x32_bf16 v[98:101], v[170:173], v[204:207], v[98:101]
	v_mfma_f32_16x16x32_bf16 v[90:93], v[188:191], v[204:207], v[90:93]
	v_mfma_f32_16x16x32_bf16 v[82:85], v[170:173], v[214:217], v[82:85]
	v_mfma_f32_16x16x32_bf16 v[74:77], v[188:191], v[214:217], v[74:77]
	v_mfma_f32_16x16x32_bf16 v[70:73], v[170:173], v[222:225], v[70:73]
	v_mfma_f32_16x16x32_bf16 v[66:69], v[188:191], v[222:225], v[66:69]
	v_mfma_f32_16x16x32_bf16 v[114:117], v[174:177], v[200:203], v[114:117]
	v_mfma_f32_16x16x32_bf16 v[106:109], v[192:195], v[200:203], v[106:109]
	v_mfma_f32_16x16x32_bf16 v[98:101], v[174:177], v[208:211], v[98:101]
	v_mfma_f32_16x16x32_bf16 v[90:93], v[192:195], v[208:211], v[90:93]
	v_mfma_f32_16x16x32_bf16 v[82:85], v[174:177], v[218:221], v[82:85]
	v_mfma_f32_16x16x32_bf16 v[74:77], v[192:195], v[218:221], v[74:77]
	v_mfma_f32_16x16x32_bf16 v[70:73], v[174:177], v[226:229], v[70:73]
	v_mfma_f32_16x16x32_bf16 v[66:69], v[192:195], v[226:229], v[66:69]
	s_barrier
	s_add_i32 s69, s54, s3
	v_lshl_add_u64 v[178:179], s[42:43], 0, v[136:137]
	s_mov_b32 m0, s69
	ds_read_b128 v[196:199], v153 offset:16384
	ds_read_b128 v[200:203], v153 offset:17408
	ds_read_b128 v[204:207], v153 offset:18432
	ds_read_b128 v[208:211], v153 offset:19456
	ds_read_b128 v[214:217], v153 offset:20480
	ds_read_b128 v[218:221], v153 offset:21504
	ds_read_b128 v[222:225], v153 offset:22528
	ds_read_b128 v[226:229], v153 offset:23552
	global_load_lds_dwordx4 v[178:179], off
	s_add_i32 m0, s69, 0x2000
	s_add_u32 s70, s42, 0x108000
	v_lshl_add_u64 v[230:231], s[42:43], 0, v[140:141]
	s_addc_u32 s71, s43, 0
	s_add_i32 s69, s55, s3
	global_load_lds_dwordx4 v[230:231], off
	v_lshl_add_u64 v[232:233], s[70:71], 0, v[136:137]
	s_mov_b32 m0, s69
	s_nop 0
	global_load_lds_dwordx4 v[232:233], off
	v_lshl_add_u64 v[232:233], s[70:71], 0, v[140:141]
	s_add_i32 m0, s69, 0x2000
	s_nop 0
	global_load_lds_dwordx4 v[232:233], off
	v_lshl_add_u64 v[232:233], s[44:45], 0, v[134:135]
	s_mov_b32 m0, s47
	s_nop 0
	global_load_lds_dwordx4 v[232:233], off
	v_lshl_add_u64 v[232:233], s[44:45], 0, v[138:139]
	s_mov_b32 m0, s48
	s_nop 0
	global_load_lds_dwordx4 v[232:233], off
	s_waitcnt vmcnt(8)
	s_waitcnt lgkmcnt(0)
	s_barrier
	s_waitcnt lgkmcnt(0)
	v_mfma_f32_16x16x32_bf16 v[62:65], v[154:157], v[196:199], v[62:65]
	v_mfma_f32_16x16x32_bf16 v[58:61], v[162:165], v[196:199], v[58:61]
	v_mfma_f32_16x16x32_bf16 v[54:57], v[154:157], v[204:207], v[54:57]
	v_mfma_f32_16x16x32_bf16 v[46:49], v[162:165], v[204:207], v[46:49]
	v_mfma_f32_16x16x32_bf16 v[38:41], v[154:157], v[214:217], v[38:41]
	v_mfma_f32_16x16x32_bf16 v[30:33], v[162:165], v[214:217], v[30:33]
	v_mfma_f32_16x16x32_bf16 v[22:25], v[154:157], v[222:225], v[22:25]
	v_mfma_f32_16x16x32_bf16 v[14:17], v[162:165], v[222:225], v[14:17]
	v_mfma_f32_16x16x32_bf16 v[62:65], v[158:161], v[200:203], v[62:65]
	v_mfma_f32_16x16x32_bf16 v[58:61], v[166:169], v[200:203], v[58:61]
	v_mfma_f32_16x16x32_bf16 v[54:57], v[158:161], v[208:211], v[54:57]
	v_mfma_f32_16x16x32_bf16 v[46:49], v[166:169], v[208:211], v[46:49]
	v_mfma_f32_16x16x32_bf16 v[38:41], v[158:161], v[218:221], v[38:41]
	v_mfma_f32_16x16x32_bf16 v[30:33], v[166:169], v[218:221], v[30:33]
	v_mfma_f32_16x16x32_bf16 v[22:25], v[158:161], v[226:229], v[22:25]
	v_mfma_f32_16x16x32_bf16 v[14:17], v[166:169], v[226:229], v[14:17]
	v_mfma_f32_16x16x32_bf16 v[50:53], v[170:173], v[196:199], v[50:53]
	v_mfma_f32_16x16x32_bf16 v[42:45], v[188:191], v[196:199], v[42:45]
	v_mfma_f32_16x16x32_bf16 v[34:37], v[170:173], v[204:207], v[34:37]
	v_mfma_f32_16x16x32_bf16 v[26:29], v[188:191], v[204:207], v[26:29]
	v_mfma_f32_16x16x32_bf16 v[18:21], v[170:173], v[214:217], v[18:21]
	v_mfma_f32_16x16x32_bf16 v[10:13], v[188:191], v[214:217], v[10:13]
	v_mfma_f32_16x16x32_bf16 v[6:9], v[170:173], v[222:225], v[6:9]
	v_mfma_f32_16x16x32_bf16 v[2:5], v[188:191], v[222:225], v[2:5]
	v_mfma_f32_16x16x32_bf16 v[50:53], v[174:177], v[200:203], v[50:53]
	v_mfma_f32_16x16x32_bf16 v[42:45], v[192:195], v[200:203], v[42:45]
	v_mfma_f32_16x16x32_bf16 v[34:37], v[174:177], v[208:211], v[34:37]
	v_mfma_f32_16x16x32_bf16 v[26:29], v[192:195], v[208:211], v[26:29]
	v_mfma_f32_16x16x32_bf16 v[18:21], v[174:177], v[218:221], v[18:21]
	v_mfma_f32_16x16x32_bf16 v[10:13], v[192:195], v[218:221], v[10:13]
	v_mfma_f32_16x16x32_bf16 v[6:9], v[174:177], v[226:229], v[6:9]
	v_mfma_f32_16x16x32_bf16 v[2:5], v[192:195], v[226:229], v[2:5]
	s_barrier
	s_add_i32 s69, 0, 0x18000
	s_add_i32 s70, 0, 0x1c000
	v_add_u32_e32 v166, s69, v133
	v_add_u32_e32 v187, s70, v133
	ds_read_b128 v[154:157], v166
	ds_read_b128 v[158:161], v166 offset:1024
	ds_read_b128 v[162:165], v166 offset:2048
	ds_read_b128 v[166:169], v166 offset:3072
	ds_read_b128 v[170:173], v187
	ds_read_b128 v[174:177], v187 offset:1024
	ds_read_b128 v[188:191], v187 offset:2048
	ds_read_b128 v[192:195], v187 offset:3072
	s_add_u32 s44, s44, 0x108000
	s_addc_u32 s45, s45, 0
	s_mov_b32 m0, s49
	v_lshl_add_u64 v[232:233], s[44:45], 0, v[134:135]
	ds_read_b128 v[196:199], v153 offset:32768
	ds_read_b128 v[200:203], v153 offset:33792
	ds_read_b128 v[204:207], v153 offset:34816
	ds_read_b128 v[208:211], v153 offset:35840
	ds_read_b128 v[214:217], v153 offset:36864
	ds_read_b128 v[218:221], v153 offset:37888
	ds_read_b128 v[222:225], v153 offset:38912
	ds_read_b128 v[226:229], v153 offset:39936
	global_load_lds_dwordx4 v[232:233], off
	v_lshl_add_u64 v[232:233], s[44:45], 0, v[138:139]
	s_mov_b32 m0, s50
	s_nop 0
	global_load_lds_dwordx4 v[232:233], off
	s_waitcnt vmcnt(8)
	s_waitcnt lgkmcnt(0)
	s_barrier
	s_waitcnt lgkmcnt(0)
	v_mfma_f32_16x16x32_bf16 v[126:129], v[154:157], v[196:199], v[126:129]
	v_mfma_f32_16x16x32_bf16 v[122:125], v[162:165], v[196:199], v[122:125]
	v_mfma_f32_16x16x32_bf16 v[118:121], v[154:157], v[204:207], v[118:121]
	v_mfma_f32_16x16x32_bf16 v[110:113], v[162:165], v[204:207], v[110:113]
	v_mfma_f32_16x16x32_bf16 v[102:105], v[154:157], v[214:217], v[102:105]
	v_mfma_f32_16x16x32_bf16 v[94:97], v[162:165], v[214:217], v[94:97]
	v_mfma_f32_16x16x32_bf16 v[86:89], v[154:157], v[222:225], v[86:89]
	v_mfma_f32_16x16x32_bf16 v[78:81], v[162:165], v[222:225], v[78:81]
	v_mfma_f32_16x16x32_bf16 v[126:129], v[158:161], v[200:203], v[126:129]
	v_mfma_f32_16x16x32_bf16 v[122:125], v[166:169], v[200:203], v[122:125]
	v_mfma_f32_16x16x32_bf16 v[118:121], v[158:161], v[208:211], v[118:121]
	v_mfma_f32_16x16x32_bf16 v[110:113], v[166:169], v[208:211], v[110:113]
	v_mfma_f32_16x16x32_bf16 v[102:105], v[158:161], v[218:221], v[102:105]
	v_mfma_f32_16x16x32_bf16 v[94:97], v[166:169], v[218:221], v[94:97]
	v_mfma_f32_16x16x32_bf16 v[86:89], v[158:161], v[226:229], v[86:89]
	v_mfma_f32_16x16x32_bf16 v[78:81], v[166:169], v[226:229], v[78:81]
	v_mfma_f32_16x16x32_bf16 v[114:117], v[170:173], v[196:199], v[114:117]
	v_mfma_f32_16x16x32_bf16 v[106:109], v[188:191], v[196:199], v[106:109]
	v_mfma_f32_16x16x32_bf16 v[98:101], v[170:173], v[204:207], v[98:101]
	v_mfma_f32_16x16x32_bf16 v[90:93], v[188:191], v[204:207], v[90:93]
	v_mfma_f32_16x16x32_bf16 v[82:85], v[170:173], v[214:217], v[82:85]
	v_mfma_f32_16x16x32_bf16 v[74:77], v[188:191], v[214:217], v[74:77]
	v_mfma_f32_16x16x32_bf16 v[70:73], v[170:173], v[222:225], v[70:73]
	v_mfma_f32_16x16x32_bf16 v[66:69], v[188:191], v[222:225], v[66:69]
	v_mfma_f32_16x16x32_bf16 v[114:117], v[174:177], v[200:203], v[114:117]
	v_mfma_f32_16x16x32_bf16 v[106:109], v[192:195], v[200:203], v[106:109]
	v_mfma_f32_16x16x32_bf16 v[98:101], v[174:177], v[208:211], v[98:101]
	v_mfma_f32_16x16x32_bf16 v[90:93], v[192:195], v[208:211], v[90:93]
	v_mfma_f32_16x16x32_bf16 v[82:85], v[174:177], v[218:221], v[82:85]
	v_mfma_f32_16x16x32_bf16 v[74:77], v[192:195], v[218:221], v[74:77]
	v_mfma_f32_16x16x32_bf16 v[70:73], v[174:177], v[226:229], v[70:73]
	v_mfma_f32_16x16x32_bf16 v[66:69], v[192:195], v[226:229], v[66:69]
	s_barrier
	s_add_i32 s44, s69, s3
	v_lshl_add_u64 v[178:179], v[178:179], 0, s[12:13]
	s_mov_b32 m0, s44
	ds_read_b128 v[196:199], v153 offset:49152
	ds_read_b128 v[200:203], v153 offset:50176
	ds_read_b128 v[204:207], v153 offset:51200
	ds_read_b128 v[208:211], v153 offset:52224
	ds_read_b128 v[214:217], v153 offset:53248
	ds_read_b128 v[218:221], v153 offset:54272
	ds_read_b128 v[222:225], v153 offset:55296
	ds_read_b128 v[226:229], v153 offset:56320
	global_load_lds_dwordx4 v[178:179], off
	s_add_i32 m0, s44, 0x2000
	s_add_u32 s42, s42, 0x108080
	v_lshl_add_u64 v[178:179], v[230:231], 0, s[12:13]
	s_addc_u32 s43, s43, 0
	s_add_i32 s44, s70, s3
	global_load_lds_dwordx4 v[178:179], off
	v_lshl_add_u64 v[178:179], s[42:43], 0, v[136:137]
	s_mov_b32 m0, s44
	s_nop 0
	global_load_lds_dwordx4 v[178:179], off
	v_lshl_add_u64 v[178:179], s[42:43], 0, v[140:141]
	s_add_i32 m0, s44, 0x2000
	s_nop 0
	global_load_lds_dwordx4 v[178:179], off
	v_lshl_add_u64 v[178:179], s[40:41], 0, v[134:135]
	s_mov_b32 m0, s52
	s_nop 0
	global_load_lds_dwordx4 v[178:179], off
	v_lshl_add_u64 v[178:179], s[40:41], 0, v[138:139]
	s_mov_b32 m0, s53
	s_nop 0
	global_load_lds_dwordx4 v[178:179], off
	s_waitcnt vmcnt(8)
	s_waitcnt lgkmcnt(0)
	s_barrier
	s_waitcnt lgkmcnt(0)
	v_mfma_f32_16x16x32_bf16 v[62:65], v[154:157], v[196:199], v[62:65]
	v_mfma_f32_16x16x32_bf16 v[58:61], v[162:165], v[196:199], v[58:61]
	v_mfma_f32_16x16x32_bf16 v[54:57], v[154:157], v[204:207], v[54:57]
	v_mfma_f32_16x16x32_bf16 v[46:49], v[162:165], v[204:207], v[46:49]
	v_mfma_f32_16x16x32_bf16 v[38:41], v[154:157], v[214:217], v[38:41]
	v_mfma_f32_16x16x32_bf16 v[30:33], v[162:165], v[214:217], v[30:33]
	v_mfma_f32_16x16x32_bf16 v[22:25], v[154:157], v[222:225], v[22:25]
	v_mfma_f32_16x16x32_bf16 v[14:17], v[162:165], v[222:225], v[14:17]
	v_mfma_f32_16x16x32_bf16 v[62:65], v[158:161], v[200:203], v[62:65]
	v_mfma_f32_16x16x32_bf16 v[58:61], v[166:169], v[200:203], v[58:61]
	v_mfma_f32_16x16x32_bf16 v[54:57], v[158:161], v[208:211], v[54:57]
	v_mfma_f32_16x16x32_bf16 v[46:49], v[166:169], v[208:211], v[46:49]
	v_mfma_f32_16x16x32_bf16 v[38:41], v[158:161], v[218:221], v[38:41]
	v_mfma_f32_16x16x32_bf16 v[30:33], v[166:169], v[218:221], v[30:33]
	v_mfma_f32_16x16x32_bf16 v[22:25], v[158:161], v[226:229], v[22:25]
	v_mfma_f32_16x16x32_bf16 v[14:17], v[166:169], v[226:229], v[14:17]
	v_mfma_f32_16x16x32_bf16 v[50:53], v[170:173], v[196:199], v[50:53]
	v_mfma_f32_16x16x32_bf16 v[42:45], v[188:191], v[196:199], v[42:45]
	v_mfma_f32_16x16x32_bf16 v[34:37], v[170:173], v[204:207], v[34:37]
	v_mfma_f32_16x16x32_bf16 v[26:29], v[188:191], v[204:207], v[26:29]
	v_mfma_f32_16x16x32_bf16 v[18:21], v[170:173], v[214:217], v[18:21]
	v_mfma_f32_16x16x32_bf16 v[10:13], v[188:191], v[214:217], v[10:13]
	v_mfma_f32_16x16x32_bf16 v[6:9], v[170:173], v[222:225], v[6:9]
	v_mfma_f32_16x16x32_bf16 v[2:5], v[188:191], v[222:225], v[2:5]
	v_mfma_f32_16x16x32_bf16 v[50:53], v[174:177], v[200:203], v[50:53]
	v_mfma_f32_16x16x32_bf16 v[42:45], v[192:195], v[200:203], v[42:45]
	v_mfma_f32_16x16x32_bf16 v[34:37], v[174:177], v[208:211], v[34:37]
	v_mfma_f32_16x16x32_bf16 v[26:29], v[192:195], v[208:211], v[26:29]
	v_mfma_f32_16x16x32_bf16 v[18:21], v[174:177], v[218:221], v[18:21]
	v_mfma_f32_16x16x32_bf16 v[10:13], v[192:195], v[218:221], v[10:13]
	v_mfma_f32_16x16x32_bf16 v[6:9], v[174:177], v[226:229], v[6:9]
	v_mfma_f32_16x16x32_bf16 v[2:5], v[192:195], v[226:229], v[2:5]
	s_barrier
	s_add_i32 s68, s68, 2
	s_add_u32 s38, s38, 0x100
	s_addc_u32 s39, s39, 0
	s_cmp_gt_u32 s68, 61
	s_cbranch_scc0 .LBB0_101
	s_and_b64 vcc, exec, s[20:21]
	s_cbranch_vccz .LBB0_104
	s_barrier

.LBB0_235:
	ds_read_b128 v[156:159], v150
	ds_read_b128 v[160:163], v150 offset:1024
	ds_read_b128 v[164:167], v150 offset:2048
	ds_read_b128 v[168:171], v150 offset:3072
	ds_read_b128 v[172:175], v151
	ds_read_b128 v[176:179], v151 offset:1024
	ds_read_b128 v[180:183], v151 offset:2048
	ds_read_b128 v[184:187], v151 offset:3072
	s_add_u32 s36, s4, s34
	s_addc_u32 s37, s5, s35
	s_add_u32 s40, s36, 0x100
	s_addc_u32 s41, s37, 0
	s_add_u32 s38, s62, s34
	s_addc_u32 s39, s63, s35
	s_add_u32 s36, s36, 0x180
	s_addc_u32 s37, s37, 0
	s_cmpk_eq_i32 s34, 0x1f00
	s_cselect_b32 s37, s61, s37
	s_cselect_b32 s36, s60, s36
	s_cselect_b32 s39, s31, s39
	s_cselect_b32 s38, s30, s38
	s_cselect_b32 s41, s23, s41
	s_cselect_b32 s40, s22, s40
	s_mov_b32 m0, s46
	v_lshl_add_u64 v[222:223], v[146:147], 0, s[34:35]
	ds_read_b128 v[188:191], v152
	ds_read_b128 v[192:195], v152 offset:1024
	ds_read_b128 v[196:199], v152 offset:2048
	ds_read_b128 v[200:203], v152 offset:3072
	ds_read_b128 v[204:207], v152 offset:4096
	ds_read_b128 v[208:211], v152 offset:5120
	ds_read_b128 v[214:217], v152 offset:6144
	ds_read_b128 v[218:221], v152 offset:7168
	global_load_lds_dwordx4 v[222:223], off
	v_lshl_add_u64 v[222:223], v[148:149], 0, s[34:35]
	s_mov_b32 m0, s47
	s_nop 0
	global_load_lds_dwordx4 v[222:223], off
	s_waitcnt vmcnt(8)
	s_waitcnt lgkmcnt(0)
	s_barrier
	s_waitcnt lgkmcnt(0)
	v_mfma_f32_16x16x32_bf16 v[126:129], v[156:159], v[188:191], v[126:129]
	v_mfma_f32_16x16x32_bf16 v[122:125], v[164:167], v[188:191], v[122:125]
	v_mfma_f32_16x16x32_bf16 v[110:113], v[156:159], v[196:199], v[110:113]
	v_mfma_f32_16x16x32_bf16 v[106:109], v[164:167], v[196:199], v[106:109]
	v_mfma_f32_16x16x32_bf16 v[94:97], v[156:159], v[204:207], v[94:97]
	v_mfma_f32_16x16x32_bf16 v[90:93], v[164:167], v[204:207], v[90:93]
	v_mfma_f32_16x16x32_bf16 v[78:81], v[156:159], v[214:217], v[78:81]
	v_mfma_f32_16x16x32_bf16 v[74:77], v[164:167], v[214:217], v[74:77]
	v_mfma_f32_16x16x32_bf16 v[126:129], v[160:163], v[192:195], v[126:129]
	v_mfma_f32_16x16x32_bf16 v[122:125], v[168:171], v[192:195], v[122:125]
	v_mfma_f32_16x16x32_bf16 v[110:113], v[160:163], v[200:203], v[110:113]
	v_mfma_f32_16x16x32_bf16 v[106:109], v[168:171], v[200:203], v[106:109]
	v_mfma_f32_16x16x32_bf16 v[94:97], v[160:163], v[208:211], v[94:97]
	v_mfma_f32_16x16x32_bf16 v[90:93], v[168:171], v[208:211], v[90:93]
	v_mfma_f32_16x16x32_bf16 v[78:81], v[160:163], v[218:221], v[78:81]
	v_mfma_f32_16x16x32_bf16 v[74:77], v[168:171], v[218:221], v[74:77]
	v_mfma_f32_16x16x32_bf16 v[118:121], v[172:175], v[188:191], v[118:121]
	v_mfma_f32_16x16x32_bf16 v[114:117], v[180:183], v[188:191], v[114:117]
	v_mfma_f32_16x16x32_bf16 v[102:105], v[172:175], v[196:199], v[102:105]
	v_mfma_f32_16x16x32_bf16 v[98:101], v[180:183], v[196:199], v[98:101]
	v_mfma_f32_16x16x32_bf16 v[86:89], v[172:175], v[204:207], v[86:89]
	v_mfma_f32_16x16x32_bf16 v[82:85], v[180:183], v[204:207], v[82:85]
	v_mfma_f32_16x16x32_bf16 v[70:73], v[172:175], v[214:217], v[70:73]
	v_mfma_f32_16x16x32_bf16 v[66:69], v[180:183], v[214:217], v[66:69]
	v_mfma_f32_16x16x32_bf16 v[118:121], v[176:179], v[192:195], v[118:121]
	v_mfma_f32_16x16x32_bf16 v[114:117], v[184:187], v[192:195], v[114:117]
	v_mfma_f32_16x16x32_bf16 v[102:105], v[176:179], v[200:203], v[102:105]
	v_mfma_f32_16x16x32_bf16 v[98:101], v[184:187], v[200:203], v[98:101]
	v_mfma_f32_16x16x32_bf16 v[86:89], v[176:179], v[208:211], v[86:89]
	v_mfma_f32_16x16x32_bf16 v[82:85], v[184:187], v[208:211], v[82:85]
	v_mfma_f32_16x16x32_bf16 v[70:73], v[176:179], v[218:221], v[70:73]
	v_mfma_f32_16x16x32_bf16 v[66:69], v[184:187], v[218:221], v[66:69]
	s_barrier
	s_mov_b32 m0, s48
	v_lshl_add_u64 v[222:223], s[38:39], 0, v[132:133]
	s_add_u32 s66, s38, 0x108000
	ds_read_b128 v[188:191], v152 offset:16384
	ds_read_b128 v[192:195], v152 offset:17408
	ds_read_b128 v[196:199], v152 offset:18432
	ds_read_b128 v[200:203], v152 offset:19456
	ds_read_b128 v[204:207], v152 offset:20480
	ds_read_b128 v[208:211], v152 offset:21504
	ds_read_b128 v[214:217], v152 offset:22528
	ds_read_b128 v[218:221], v152 offset:23552
	global_load_lds_dwordx4 v[222:223], off
	v_lshl_add_u64 v[224:225], s[38:39], 0, v[136:137]
	s_mov_b32 m0, s49
	s_addc_u32 s67, s39, 0
	global_load_lds_dwordx4 v[224:225], off
	v_lshl_add_u64 v[226:227], s[66:67], 0, v[132:133]
	s_mov_b32 m0, s50
	s_nop 0
	global_load_lds_dwordx4 v[226:227], off
	v_lshl_add_u64 v[226:227], s[66:67], 0, v[136:137]
	s_mov_b32 m0, s51
	s_nop 0
	global_load_lds_dwordx4 v[226:227], off
	v_lshl_add_u64 v[226:227], s[40:41], 0, v[130:131]
	s_mov_b32 m0, s3
	s_nop 0
	global_load_lds_dwordx4 v[226:227], off
	v_lshl_add_u64 v[226:227], s[40:41], 0, v[134:135]
	s_mov_b32 m0, s33
	s_nop 0
	global_load_lds_dwordx4 v[226:227], off
	s_waitcnt vmcnt(8)
	s_waitcnt lgkmcnt(0)
	s_barrier
	s_waitcnt lgkmcnt(0)
	v_mfma_f32_16x16x32_bf16 v[62:65], v[156:159], v[188:191], v[62:65]
	v_mfma_f32_16x16x32_bf16 v[58:61], v[164:167], v[188:191], v[58:61]
	v_mfma_f32_16x16x32_bf16 v[46:49], v[156:159], v[196:199], v[46:49]
	v_mfma_f32_16x16x32_bf16 v[42:45], v[164:167], v[196:199], v[42:45]
	v_mfma_f32_16x16x32_bf16 v[30:33], v[156:159], v[204:207], v[30:33]
	v_mfma_f32_16x16x32_bf16 v[26:29], v[164:167], v[204:207], v[26:29]
	v_mfma_f32_16x16x32_bf16 v[14:17], v[156:159], v[214:217], v[14:17]
	v_mfma_f32_16x16x32_bf16 v[10:13], v[164:167], v[214:217], v[10:13]
	v_mfma_f32_16x16x32_bf16 v[62:65], v[160:163], v[192:195], v[62:65]
	v_mfma_f32_16x16x32_bf16 v[58:61], v[168:171], v[192:195], v[58:61]
	v_mfma_f32_16x16x32_bf16 v[46:49], v[160:163], v[200:203], v[46:49]
	v_mfma_f32_16x16x32_bf16 v[42:45], v[168:171], v[200:203], v[42:45]
	v_mfma_f32_16x16x32_bf16 v[30:33], v[160:163], v[208:211], v[30:33]
	v_mfma_f32_16x16x32_bf16 v[26:29], v[168:171], v[208:211], v[26:29]
	v_mfma_f32_16x16x32_bf16 v[14:17], v[160:163], v[218:221], v[14:17]
	v_mfma_f32_16x16x32_bf16 v[10:13], v[168:171], v[218:221], v[10:13]
	v_mfma_f32_16x16x32_bf16 v[54:57], v[172:175], v[188:191], v[54:57]
	v_mfma_f32_16x16x32_bf16 v[50:53], v[180:183], v[188:191], v[50:53]
	v_mfma_f32_16x16x32_bf16 v[38:41], v[172:175], v[196:199], v[38:41]
	v_mfma_f32_16x16x32_bf16 v[34:37], v[180:183], v[196:199], v[34:37]
	v_mfma_f32_16x16x32_bf16 v[22:25], v[172:175], v[204:207], v[22:25]
	v_mfma_f32_16x16x32_bf16 v[18:21], v[180:183], v[204:207], v[18:21]
	v_mfma_f32_16x16x32_bf16 v[6:9], v[172:175], v[214:217], v[6:9]
	v_mfma_f32_16x16x32_bf16 v[2:5], v[180:183], v[214:217], v[2:5]
	v_mfma_f32_16x16x32_bf16 v[54:57], v[176:179], v[192:195], v[54:57]
	v_mfma_f32_16x16x32_bf16 v[50:53], v[184:187], v[192:195], v[50:53]
	v_mfma_f32_16x16x32_bf16 v[38:41], v[176:179], v[200:203], v[38:41]
	v_mfma_f32_16x16x32_bf16 v[34:37], v[184:187], v[200:203], v[34:37]
	v_mfma_f32_16x16x32_bf16 v[22:25], v[176:179], v[208:211], v[22:25]
	v_mfma_f32_16x16x32_bf16 v[18:21], v[184:187], v[208:211], v[18:21]
	v_mfma_f32_16x16x32_bf16 v[6:9], v[176:179], v[218:221], v[6:9]
	v_mfma_f32_16x16x32_bf16 v[2:5], v[184:187], v[218:221], v[2:5]
	s_barrier
	ds_read_b128 v[156:159], v153
	ds_read_b128 v[160:163], v153 offset:1024
	ds_read_b128 v[164:167], v153 offset:2048
	ds_read_b128 v[168:171], v153 offset:3072
	ds_read_b128 v[172:175], v154
	ds_read_b128 v[176:179], v154 offset:1024
	ds_read_b128 v[180:183], v154 offset:2048
	ds_read_b128 v[184:187], v154 offset:3072
	s_add_u32 s40, s40, 0x108000
	s_addc_u32 s41, s41, 0
	s_mov_b32 m0, s42
	v_lshl_add_u64 v[226:227], s[40:41], 0, v[130:131]
	ds_read_b128 v[188:191], v152 offset:32768
	ds_read_b128 v[192:195], v152 offset:33792
	ds_read_b128 v[196:199], v152 offset:34816
	ds_read_b128 v[200:203], v152 offset:35840
	ds_read_b128 v[204:207], v152 offset:36864
	ds_read_b128 v[208:211], v152 offset:37888
	ds_read_b128 v[214:217], v152 offset:38912
	ds_read_b128 v[218:221], v152 offset:39936
	global_load_lds_dwordx4 v[226:227], off
	v_lshl_add_u64 v[226:227], s[40:41], 0, v[134:135]
	s_mov_b32 m0, s43
	s_nop 0
	global_load_lds_dwordx4 v[226:227], off
	s_waitcnt vmcnt(8)
	s_waitcnt lgkmcnt(0)
	s_barrier
	s_waitcnt lgkmcnt(0)
	v_mfma_f32_16x16x32_bf16 v[126:129], v[156:159], v[188:191], v[126:129]
	v_mfma_f32_16x16x32_bf16 v[122:125], v[164:167], v[188:191], v[122:125]
	v_mfma_f32_16x16x32_bf16 v[110:113], v[156:159], v[196:199], v[110:113]
	v_mfma_f32_16x16x32_bf16 v[106:109], v[164:167], v[196:199], v[106:109]
	v_mfma_f32_16x16x32_bf16 v[94:97], v[156:159], v[204:207], v[94:97]
	v_mfma_f32_16x16x32_bf16 v[90:93], v[164:167], v[204:207], v[90:93]
	v_mfma_f32_16x16x32_bf16 v[78:81], v[156:159], v[214:217], v[78:81]
	v_mfma_f32_16x16x32_bf16 v[74:77], v[164:167], v[214:217], v[74:77]
	v_mfma_f32_16x16x32_bf16 v[126:129], v[160:163], v[192:195], v[126:129]
	v_mfma_f32_16x16x32_bf16 v[122:125], v[168:171], v[192:195], v[122:125]
	v_mfma_f32_16x16x32_bf16 v[110:113], v[160:163], v[200:203], v[110:113]
	v_mfma_f32_16x16x32_bf16 v[106:109], v[168:171], v[200:203], v[106:109]
	v_mfma_f32_16x16x32_bf16 v[94:97], v[160:163], v[208:211], v[94:97]
	v_mfma_f32_16x16x32_bf16 v[90:93], v[168:171], v[208:211], v[90:93]
	v_mfma_f32_16x16x32_bf16 v[78:81], v[160:163], v[218:221], v[78:81]
	v_mfma_f32_16x16x32_bf16 v[74:77], v[168:171], v[218:221], v[74:77]
	v_mfma_f32_16x16x32_bf16 v[118:121], v[172:175], v[188:191], v[118:121]
	v_mfma_f32_16x16x32_bf16 v[114:117], v[180:183], v[188:191], v[114:117]
	v_mfma_f32_16x16x32_bf16 v[102:105], v[172:175], v[196:199], v[102:105]
	v_mfma_f32_16x16x32_bf16 v[98:101], v[180:183], v[196:199], v[98:101]
	v_mfma_f32_16x16x32_bf16 v[86:89], v[172:175], v[204:207], v[86:89]
	v_mfma_f32_16x16x32_bf16 v[82:85], v[180:183], v[204:207], v[82:85]
	v_mfma_f32_16x16x32_bf16 v[70:73], v[172:175], v[214:217], v[70:73]
	v_mfma_f32_16x16x32_bf16 v[66:69], v[180:183], v[214:217], v[66:69]
	v_mfma_f32_16x16x32_bf16 v[118:121], v[176:179], v[192:195], v[118:121]
	v_mfma_f32_16x16x32_bf16 v[114:117], v[184:187], v[192:195], v[114:117]
	v_mfma_f32_16x16x32_bf16 v[102:105], v[176:179], v[200:203], v[102:105]
	v_mfma_f32_16x16x32_bf16 v[98:101], v[184:187], v[200:203], v[98:101]
	v_mfma_f32_16x16x32_bf16 v[86:89], v[176:179], v[208:211], v[86:89]
	v_mfma_f32_16x16x32_bf16 v[82:85], v[184:187], v[208:211], v[82:85]
	v_mfma_f32_16x16x32_bf16 v[70:73], v[176:179], v[218:221], v[70:73]
	v_mfma_f32_16x16x32_bf16 v[66:69], v[184:187], v[218:221], v[66:69]
	s_barrier
	s_mov_b32 m0, s53
	v_lshl_add_u64 v[222:223], v[222:223], 0, s[16:17]
	s_add_u32 s38, s38, 0x108080
	ds_read_b128 v[188:191], v152 offset:49152
	ds_read_b128 v[192:195], v152 offset:50176
	ds_read_b128 v[196:199], v152 offset:51200
	ds_read_b128 v[200:203], v152 offset:52224
	ds_read_b128 v[204:207], v152 offset:53248
	ds_read_b128 v[208:211], v152 offset:54272
	ds_read_b128 v[214:217], v152 offset:55296
	ds_read_b128 v[218:221], v152 offset:56320
	global_load_lds_dwordx4 v[222:223], off
	v_lshl_add_u64 v[222:223], v[224:225], 0, s[16:17]
	s_mov_b32 m0, s54
	s_addc_u32 s39, s39, 0
	s_add_i32 s40, s52, s2
	global_load_lds_dwordx4 v[222:223], off
	v_lshl_add_u64 v[222:223], s[38:39], 0, v[132:133]
	s_mov_b32 m0, s40
	s_nop 0
	global_load_lds_dwordx4 v[222:223], off
	v_lshl_add_u64 v[222:223], s[38:39], 0, v[136:137]
	s_add_i32 m0, s40, 0x2000
	s_nop 0
	global_load_lds_dwordx4 v[222:223], off
	v_lshl_add_u64 v[222:223], s[36:37], 0, v[130:131]
	s_mov_b32 m0, s44
	s_nop 0
	global_load_lds_dwordx4 v[222:223], off
	v_lshl_add_u64 v[222:223], s[36:37], 0, v[134:135]
	s_mov_b32 m0, s45
	s_nop 0
	global_load_lds_dwordx4 v[222:223], off
	s_waitcnt vmcnt(8)
	s_waitcnt lgkmcnt(0)
	s_barrier
	s_waitcnt lgkmcnt(0)
	v_mfma_f32_16x16x32_bf16 v[62:65], v[156:159], v[188:191], v[62:65]
	v_mfma_f32_16x16x32_bf16 v[58:61], v[164:167], v[188:191], v[58:61]
	v_mfma_f32_16x16x32_bf16 v[46:49], v[156:159], v[196:199], v[46:49]
	v_mfma_f32_16x16x32_bf16 v[42:45], v[164:167], v[196:199], v[42:45]
	v_mfma_f32_16x16x32_bf16 v[30:33], v[156:159], v[204:207], v[30:33]
	v_mfma_f32_16x16x32_bf16 v[26:29], v[164:167], v[204:207], v[26:29]
	v_mfma_f32_16x16x32_bf16 v[14:17], v[156:159], v[214:217], v[14:17]
	v_mfma_f32_16x16x32_bf16 v[10:13], v[164:167], v[214:217], v[10:13]
	v_mfma_f32_16x16x32_bf16 v[62:65], v[160:163], v[192:195], v[62:65]
	v_mfma_f32_16x16x32_bf16 v[58:61], v[168:171], v[192:195], v[58:61]
	v_mfma_f32_16x16x32_bf16 v[46:49], v[160:163], v[200:203], v[46:49]
	v_mfma_f32_16x16x32_bf16 v[42:45], v[168:171], v[200:203], v[42:45]
	v_mfma_f32_16x16x32_bf16 v[30:33], v[160:163], v[208:211], v[30:33]
	v_mfma_f32_16x16x32_bf16 v[26:29], v[168:171], v[208:211], v[26:29]
	v_mfma_f32_16x16x32_bf16 v[14:17], v[160:163], v[218:221], v[14:17]
	v_mfma_f32_16x16x32_bf16 v[10:13], v[168:171], v[218:221], v[10:13]
	v_mfma_f32_16x16x32_bf16 v[54:57], v[172:175], v[188:191], v[54:57]
	v_mfma_f32_16x16x32_bf16 v[50:53], v[180:183], v[188:191], v[50:53]
	v_mfma_f32_16x16x32_bf16 v[38:41], v[172:175], v[196:199], v[38:41]
	v_mfma_f32_16x16x32_bf16 v[34:37], v[180:183], v[196:199], v[34:37]
	v_mfma_f32_16x16x32_bf16 v[22:25], v[172:175], v[204:207], v[22:25]
	v_mfma_f32_16x16x32_bf16 v[18:21], v[180:183], v[204:207], v[18:21]
	v_mfma_f32_16x16x32_bf16 v[6:9], v[172:175], v[214:217], v[6:9]
	v_mfma_f32_16x16x32_bf16 v[2:5], v[180:183], v[214:217], v[2:5]
	v_mfma_f32_16x16x32_bf16 v[54:57], v[176:179], v[192:195], v[54:57]
	v_mfma_f32_16x16x32_bf16 v[50:53], v[184:187], v[192:195], v[50:53]
	v_mfma_f32_16x16x32_bf16 v[38:41], v[176:179], v[200:203], v[38:41]
	v_mfma_f32_16x16x32_bf16 v[34:37], v[184:187], v[200:203], v[34:37]
	v_mfma_f32_16x16x32_bf16 v[22:25], v[176:179], v[208:211], v[22:25]
	v_mfma_f32_16x16x32_bf16 v[18:21], v[184:187], v[208:211], v[18:21]
	v_mfma_f32_16x16x32_bf16 v[6:9], v[176:179], v[218:221], v[6:9]
	v_mfma_f32_16x16x32_bf16 v[2:5], v[184:187], v[218:221], v[2:5]
	s_barrier
	s_add_i32 s64, s64, 2
	s_add_u32 s34, s34, 0x100
	s_addc_u32 s35, s35, 0
	s_cmp_gt_u32 s64, 61
	s_cbranch_scc0 .LBB0_235
	s_and_b64 vcc, exec, s[20:21]
	s_cbranch_vccz .LBB0_238
	s_barrier

.LBB0_434:
	ds_read_b128 v[134:137], v204
	ds_read_b128 v[138:141], v204 offset:1024
	ds_read_b128 v[142:145], v204 offset:2048
	ds_read_b128 v[146:149], v204 offset:3072
	ds_read_b128 v[150:153], v205
	ds_read_b128 v[154:157], v205 offset:1024
	ds_read_b128 v[158:161], v205 offset:2048
	ds_read_b128 v[162:165], v205 offset:3072
	s_add_u32 s34, s22, s30
	s_addc_u32 s35, s23, s31
	s_add_u32 s38, s34, 0x100
	s_addc_u32 s39, s35, 0
	s_add_u32 s36, s60, s30
	s_addc_u32 s37, s61, s31
	s_add_u32 s34, s34, 0x180
	s_addc_u32 s35, s35, 0
	s_cmpk_eq_i32 s30, 0xb00
	s_cselect_b32 s35, s59, s35
	s_cselect_b32 s34, s58, s34
	s_cselect_b32 s37, s21, s37
	s_cselect_b32 s36, s20, s36
	s_cselect_b32 s39, s17, s39
	s_cselect_b32 s38, s16, s38
	v_lshl_add_u64 v[200:201], v[130:131], 0, s[30:31]
	s_add_i32 m0, s3, 0xc000
	ds_read_b128 v[166:169], v206
	ds_read_b128 v[170:173], v206 offset:1024
	ds_read_b128 v[174:177], v206 offset:2048
	ds_read_b128 v[178:181], v206 offset:3072
	ds_read_b128 v[182:185], v206 offset:4096
	ds_read_b128 v[208:211], v206 offset:5120
	ds_read_b128 v[214:217], v206 offset:6144
	ds_read_b128 v[218:221], v206 offset:7168
	global_load_lds_dwordx4 v[200:201], off
	v_lshl_add_u64 v[200:201], v[132:133], 0, s[30:31]
	s_add_i32 m0, s3, 0xe000
	s_nop 0
	global_load_lds_dwordx4 v[200:201], off
	s_waitcnt vmcnt(8)
	s_waitcnt lgkmcnt(0)
	s_barrier
	s_waitcnt lgkmcnt(0)
	v_mfma_f32_16x16x32_bf16 v[126:129], v[134:137], v[166:169], v[126:129]
	v_mfma_f32_16x16x32_bf16 v[122:125], v[142:145], v[166:169], v[122:125]
	v_mfma_f32_16x16x32_bf16 v[110:113], v[134:137], v[174:177], v[110:113]
	v_mfma_f32_16x16x32_bf16 v[106:109], v[142:145], v[174:177], v[106:109]
	v_mfma_f32_16x16x32_bf16 v[94:97], v[134:137], v[182:185], v[94:97]
	v_mfma_f32_16x16x32_bf16 v[90:93], v[142:145], v[182:185], v[90:93]
	v_mfma_f32_16x16x32_bf16 v[78:81], v[134:137], v[214:217], v[78:81]
	v_mfma_f32_16x16x32_bf16 v[74:77], v[142:145], v[214:217], v[74:77]
	v_mfma_f32_16x16x32_bf16 v[126:129], v[138:141], v[170:173], v[126:129]
	v_mfma_f32_16x16x32_bf16 v[122:125], v[146:149], v[170:173], v[122:125]
	v_mfma_f32_16x16x32_bf16 v[110:113], v[138:141], v[178:181], v[110:113]
	v_mfma_f32_16x16x32_bf16 v[106:109], v[146:149], v[178:181], v[106:109]
	v_mfma_f32_16x16x32_bf16 v[94:97], v[138:141], v[208:211], v[94:97]
	v_mfma_f32_16x16x32_bf16 v[90:93], v[146:149], v[208:211], v[90:93]
	v_mfma_f32_16x16x32_bf16 v[78:81], v[138:141], v[218:221], v[78:81]
	v_mfma_f32_16x16x32_bf16 v[74:77], v[146:149], v[218:221], v[74:77]
	v_mfma_f32_16x16x32_bf16 v[118:121], v[150:153], v[166:169], v[118:121]
	v_mfma_f32_16x16x32_bf16 v[114:117], v[158:161], v[166:169], v[114:117]
	v_mfma_f32_16x16x32_bf16 v[102:105], v[150:153], v[174:177], v[102:105]
	v_mfma_f32_16x16x32_bf16 v[98:101], v[158:161], v[174:177], v[98:101]
	v_mfma_f32_16x16x32_bf16 v[86:89], v[150:153], v[182:185], v[86:89]
	v_mfma_f32_16x16x32_bf16 v[82:85], v[158:161], v[182:185], v[82:85]
	v_mfma_f32_16x16x32_bf16 v[70:73], v[150:153], v[214:217], v[70:73]
	v_mfma_f32_16x16x32_bf16 v[66:69], v[158:161], v[214:217], v[66:69]
	v_mfma_f32_16x16x32_bf16 v[118:121], v[154:157], v[170:173], v[118:121]
	v_mfma_f32_16x16x32_bf16 v[114:117], v[162:165], v[170:173], v[114:117]
	v_mfma_f32_16x16x32_bf16 v[102:105], v[154:157], v[178:181], v[102:105]
	v_mfma_f32_16x16x32_bf16 v[98:101], v[162:165], v[178:181], v[98:101]
	v_mfma_f32_16x16x32_bf16 v[86:89], v[154:157], v[208:211], v[86:89]
	v_mfma_f32_16x16x32_bf16 v[82:85], v[162:165], v[208:211], v[82:85]
	v_mfma_f32_16x16x32_bf16 v[70:73], v[154:157], v[218:221], v[70:73]
	v_mfma_f32_16x16x32_bf16 v[66:69], v[162:165], v[218:221], v[66:69]
	s_barrier
	s_add_i32 s63, s52, s2
	v_lshl_add_u64 v[200:201], s[36:37], 0, v[188:189]
	s_mov_b32 m0, s63
	ds_read_b128 v[166:169], v206 offset:16384
	ds_read_b128 v[170:173], v206 offset:17408
	ds_read_b128 v[174:177], v206 offset:18432
	ds_read_b128 v[178:181], v206 offset:19456
	ds_read_b128 v[182:185], v206 offset:20480
	ds_read_b128 v[208:211], v206 offset:21504
	ds_read_b128 v[214:217], v206 offset:22528
	ds_read_b128 v[218:221], v206 offset:23552
	global_load_lds_dwordx4 v[200:201], off
	s_add_i32 m0, s63, 0x2000
	s_add_u32 s64, s36, 0x68000
	v_lshl_add_u64 v[222:223], s[36:37], 0, v[192:193]
	s_addc_u32 s65, s37, 0
	s_add_i32 s63, s53, s2
	global_load_lds_dwordx4 v[222:223], off
	v_lshl_add_u64 v[224:225], s[64:65], 0, v[188:189]
	s_mov_b32 m0, s63
	s_nop 0
	global_load_lds_dwordx4 v[224:225], off
	v_lshl_add_u64 v[224:225], s[64:65], 0, v[192:193]
	s_add_i32 m0, s63, 0x2000
	s_nop 0
	global_load_lds_dwordx4 v[224:225], off
	v_lshl_add_u64 v[224:225], s[38:39], 0, v[186:187]
	s_mov_b32 m0, s3
	s_nop 0
	global_load_lds_dwordx4 v[224:225], off
	v_lshl_add_u64 v[224:225], s[38:39], 0, v[190:191]
	s_mov_b32 m0, s33
	s_nop 0
	global_load_lds_dwordx4 v[224:225], off
	s_waitcnt vmcnt(8)
	s_waitcnt lgkmcnt(0)
	s_barrier
	s_waitcnt lgkmcnt(0)
	v_mfma_f32_16x16x32_bf16 v[62:65], v[134:137], v[166:169], v[62:65]
	v_mfma_f32_16x16x32_bf16 v[58:61], v[142:145], v[166:169], v[58:61]
	v_mfma_f32_16x16x32_bf16 v[46:49], v[134:137], v[174:177], v[46:49]
	v_mfma_f32_16x16x32_bf16 v[42:45], v[142:145], v[174:177], v[42:45]
	v_mfma_f32_16x16x32_bf16 v[30:33], v[134:137], v[182:185], v[30:33]
	v_mfma_f32_16x16x32_bf16 v[26:29], v[142:145], v[182:185], v[26:29]
	v_mfma_f32_16x16x32_bf16 v[14:17], v[134:137], v[214:217], v[14:17]
	v_mfma_f32_16x16x32_bf16 v[10:13], v[142:145], v[214:217], v[10:13]
	v_mfma_f32_16x16x32_bf16 v[62:65], v[138:141], v[170:173], v[62:65]
	v_mfma_f32_16x16x32_bf16 v[58:61], v[146:149], v[170:173], v[58:61]
	v_mfma_f32_16x16x32_bf16 v[46:49], v[138:141], v[178:181], v[46:49]
	v_mfma_f32_16x16x32_bf16 v[42:45], v[146:149], v[178:181], v[42:45]
	v_mfma_f32_16x16x32_bf16 v[30:33], v[138:141], v[208:211], v[30:33]
	v_mfma_f32_16x16x32_bf16 v[26:29], v[146:149], v[208:211], v[26:29]
	v_mfma_f32_16x16x32_bf16 v[14:17], v[138:141], v[218:221], v[14:17]
	v_mfma_f32_16x16x32_bf16 v[10:13], v[146:149], v[218:221], v[10:13]
	v_mfma_f32_16x16x32_bf16 v[54:57], v[150:153], v[166:169], v[54:57]
	v_mfma_f32_16x16x32_bf16 v[50:53], v[158:161], v[166:169], v[50:53]
	v_mfma_f32_16x16x32_bf16 v[38:41], v[150:153], v[174:177], v[38:41]
	v_mfma_f32_16x16x32_bf16 v[34:37], v[158:161], v[174:177], v[34:37]
	v_mfma_f32_16x16x32_bf16 v[22:25], v[150:153], v[182:185], v[22:25]
	v_mfma_f32_16x16x32_bf16 v[18:21], v[158:161], v[182:185], v[18:21]
	v_mfma_f32_16x16x32_bf16 v[6:9], v[150:153], v[214:217], v[6:9]
	v_mfma_f32_16x16x32_bf16 v[2:5], v[158:161], v[214:217], v[2:5]
	v_mfma_f32_16x16x32_bf16 v[54:57], v[154:157], v[170:173], v[54:57]
	v_mfma_f32_16x16x32_bf16 v[50:53], v[162:165], v[170:173], v[50:53]
	v_mfma_f32_16x16x32_bf16 v[38:41], v[154:157], v[178:181], v[38:41]
	v_mfma_f32_16x16x32_bf16 v[34:37], v[162:165], v[178:181], v[34:37]
	v_mfma_f32_16x16x32_bf16 v[22:25], v[154:157], v[208:211], v[22:25]
	v_mfma_f32_16x16x32_bf16 v[18:21], v[162:165], v[208:211], v[18:21]
	v_mfma_f32_16x16x32_bf16 v[6:9], v[154:157], v[218:221], v[6:9]
	v_mfma_f32_16x16x32_bf16 v[2:5], v[162:165], v[218:221], v[2:5]
	s_barrier
	s_add_i32 s63, 0, 0x18000
	s_add_i32 s64, 0, 0x1c000
	v_add_u32_e32 v146, s63, v202
	v_add_u32_e32 v162, s64, v202
	ds_read_b128 v[134:137], v146
	ds_read_b128 v[138:141], v146 offset:1024
	ds_read_b128 v[142:145], v146 offset:2048
	ds_read_b128 v[146:149], v146 offset:3072
	ds_read_b128 v[150:153], v162
	ds_read_b128 v[154:157], v162 offset:1024
	ds_read_b128 v[158:161], v162 offset:2048
	ds_read_b128 v[162:165], v162 offset:3072
	s_add_u32 s38, s38, 0x188000
	s_addc_u32 s39, s39, 0
	s_mov_b32 m0, s40
	v_lshl_add_u64 v[224:225], s[38:39], 0, v[186:187]
	ds_read_b128 v[166:169], v206 offset:32768
	ds_read_b128 v[170:173], v206 offset:33792
	ds_read_b128 v[174:177], v206 offset:34816
	ds_read_b128 v[178:181], v206 offset:35840
	ds_read_b128 v[182:185], v206 offset:36864
	ds_read_b128 v[208:211], v206 offset:37888
	ds_read_b128 v[214:217], v206 offset:38912
	ds_read_b128 v[218:221], v206 offset:39936
	global_load_lds_dwordx4 v[224:225], off
	v_lshl_add_u64 v[224:225], s[38:39], 0, v[190:191]
	s_mov_b32 m0, s41
	s_nop 0
	global_load_lds_dwordx4 v[224:225], off
	s_waitcnt vmcnt(8)
	s_waitcnt lgkmcnt(0)
	s_barrier
	s_waitcnt lgkmcnt(0)
	v_mfma_f32_16x16x32_bf16 v[126:129], v[134:137], v[166:169], v[126:129]
	v_mfma_f32_16x16x32_bf16 v[122:125], v[142:145], v[166:169], v[122:125]
	v_mfma_f32_16x16x32_bf16 v[110:113], v[134:137], v[174:177], v[110:113]
	v_mfma_f32_16x16x32_bf16 v[106:109], v[142:145], v[174:177], v[106:109]
	v_mfma_f32_16x16x32_bf16 v[94:97], v[134:137], v[182:185], v[94:97]
	v_mfma_f32_16x16x32_bf16 v[90:93], v[142:145], v[182:185], v[90:93]
	v_mfma_f32_16x16x32_bf16 v[78:81], v[134:137], v[214:217], v[78:81]
	v_mfma_f32_16x16x32_bf16 v[74:77], v[142:145], v[214:217], v[74:77]
	v_mfma_f32_16x16x32_bf16 v[126:129], v[138:141], v[170:173], v[126:129]
	v_mfma_f32_16x16x32_bf16 v[122:125], v[146:149], v[170:173], v[122:125]
	v_mfma_f32_16x16x32_bf16 v[110:113], v[138:141], v[178:181], v[110:113]
	v_mfma_f32_16x16x32_bf16 v[106:109], v[146:149], v[178:181], v[106:109]
	v_mfma_f32_16x16x32_bf16 v[94:97], v[138:141], v[208:211], v[94:97]
	v_mfma_f32_16x16x32_bf16 v[90:93], v[146:149], v[208:211], v[90:93]
	v_mfma_f32_16x16x32_bf16 v[78:81], v[138:141], v[218:221], v[78:81]
	v_mfma_f32_16x16x32_bf16 v[74:77], v[146:149], v[218:221], v[74:77]
	v_mfma_f32_16x16x32_bf16 v[118:121], v[150:153], v[166:169], v[118:121]
	v_mfma_f32_16x16x32_bf16 v[114:117], v[158:161], v[166:169], v[114:117]
	v_mfma_f32_16x16x32_bf16 v[102:105], v[150:153], v[174:177], v[102:105]
	v_mfma_f32_16x16x32_bf16 v[98:101], v[158:161], v[174:177], v[98:101]
	v_mfma_f32_16x16x32_bf16 v[86:89], v[150:153], v[182:185], v[86:89]
	v_mfma_f32_16x16x32_bf16 v[82:85], v[158:161], v[182:185], v[82:85]
	v_mfma_f32_16x16x32_bf16 v[70:73], v[150:153], v[214:217], v[70:73]
	v_mfma_f32_16x16x32_bf16 v[66:69], v[158:161], v[214:217], v[66:69]
	v_mfma_f32_16x16x32_bf16 v[118:121], v[154:157], v[170:173], v[118:121]
	v_mfma_f32_16x16x32_bf16 v[114:117], v[162:165], v[170:173], v[114:117]
	v_mfma_f32_16x16x32_bf16 v[102:105], v[154:157], v[178:181], v[102:105]
	v_mfma_f32_16x16x32_bf16 v[98:101], v[162:165], v[178:181], v[98:101]
	v_mfma_f32_16x16x32_bf16 v[86:89], v[154:157], v[208:211], v[86:89]
	v_mfma_f32_16x16x32_bf16 v[82:85], v[162:165], v[208:211], v[82:85]
	v_mfma_f32_16x16x32_bf16 v[70:73], v[154:157], v[218:221], v[70:73]
	v_mfma_f32_16x16x32_bf16 v[66:69], v[162:165], v[218:221], v[66:69]
	s_barrier
	s_add_i32 s38, s63, s2
	v_lshl_add_u64 v[200:201], v[200:201], 0, s[12:13]
	s_mov_b32 m0, s38
	ds_read_b128 v[166:169], v206 offset:49152
	ds_read_b128 v[170:173], v206 offset:50176
	ds_read_b128 v[174:177], v206 offset:51200
	ds_read_b128 v[178:181], v206 offset:52224
	ds_read_b128 v[182:185], v206 offset:53248
	ds_read_b128 v[208:211], v206 offset:54272
	ds_read_b128 v[214:217], v206 offset:55296
	ds_read_b128 v[218:221], v206 offset:56320
	global_load_lds_dwordx4 v[200:201], off
	s_add_i32 m0, s38, 0x2000
	s_add_u32 s36, s36, 0x68080
	v_lshl_add_u64 v[200:201], v[222:223], 0, s[12:13]
	s_addc_u32 s37, s37, 0
	s_add_i32 s38, s64, s2
	global_load_lds_dwordx4 v[200:201], off
	v_lshl_add_u64 v[200:201], s[36:37], 0, v[188:189]
	s_mov_b32 m0, s38
	s_nop 0
	global_load_lds_dwordx4 v[200:201], off
	v_lshl_add_u64 v[200:201], s[36:37], 0, v[192:193]
	s_add_i32 m0, s38, 0x2000
	s_nop 0
	global_load_lds_dwordx4 v[200:201], off
	v_lshl_add_u64 v[200:201], s[34:35], 0, v[186:187]
	s_mov_b32 m0, s50
	s_nop 0
	global_load_lds_dwordx4 v[200:201], off
	v_lshl_add_u64 v[200:201], s[34:35], 0, v[190:191]
	s_mov_b32 m0, s51
	s_nop 0
	global_load_lds_dwordx4 v[200:201], off
	s_waitcnt vmcnt(8)
	s_waitcnt lgkmcnt(0)
	s_barrier
	s_waitcnt lgkmcnt(0)
	v_mfma_f32_16x16x32_bf16 v[62:65], v[134:137], v[166:169], v[62:65]
	v_mfma_f32_16x16x32_bf16 v[58:61], v[142:145], v[166:169], v[58:61]
	v_mfma_f32_16x16x32_bf16 v[46:49], v[134:137], v[174:177], v[46:49]
	v_mfma_f32_16x16x32_bf16 v[42:45], v[142:145], v[174:177], v[42:45]
	v_mfma_f32_16x16x32_bf16 v[30:33], v[134:137], v[182:185], v[30:33]
	v_mfma_f32_16x16x32_bf16 v[26:29], v[142:145], v[182:185], v[26:29]
	v_mfma_f32_16x16x32_bf16 v[14:17], v[134:137], v[214:217], v[14:17]
	v_mfma_f32_16x16x32_bf16 v[10:13], v[142:145], v[214:217], v[10:13]
	v_mfma_f32_16x16x32_bf16 v[62:65], v[138:141], v[170:173], v[62:65]
	v_mfma_f32_16x16x32_bf16 v[58:61], v[146:149], v[170:173], v[58:61]
	v_mfma_f32_16x16x32_bf16 v[46:49], v[138:141], v[178:181], v[46:49]
	v_mfma_f32_16x16x32_bf16 v[42:45], v[146:149], v[178:181], v[42:45]
	v_mfma_f32_16x16x32_bf16 v[30:33], v[138:141], v[208:211], v[30:33]
	v_mfma_f32_16x16x32_bf16 v[26:29], v[146:149], v[208:211], v[26:29]
	v_mfma_f32_16x16x32_bf16 v[14:17], v[138:141], v[218:221], v[14:17]
	v_mfma_f32_16x16x32_bf16 v[10:13], v[146:149], v[218:221], v[10:13]
	v_mfma_f32_16x16x32_bf16 v[54:57], v[150:153], v[166:169], v[54:57]
	v_mfma_f32_16x16x32_bf16 v[50:53], v[158:161], v[166:169], v[50:53]
	v_mfma_f32_16x16x32_bf16 v[38:41], v[150:153], v[174:177], v[38:41]
	v_mfma_f32_16x16x32_bf16 v[34:37], v[158:161], v[174:177], v[34:37]
	v_mfma_f32_16x16x32_bf16 v[22:25], v[150:153], v[182:185], v[22:25]
	v_mfma_f32_16x16x32_bf16 v[18:21], v[158:161], v[182:185], v[18:21]
	v_mfma_f32_16x16x32_bf16 v[6:9], v[150:153], v[214:217], v[6:9]
	v_mfma_f32_16x16x32_bf16 v[2:5], v[158:161], v[214:217], v[2:5]
	v_mfma_f32_16x16x32_bf16 v[54:57], v[154:157], v[170:173], v[54:57]
	v_mfma_f32_16x16x32_bf16 v[50:53], v[162:165], v[170:173], v[50:53]
	v_mfma_f32_16x16x32_bf16 v[38:41], v[154:157], v[178:181], v[38:41]
	v_mfma_f32_16x16x32_bf16 v[34:37], v[162:165], v[178:181], v[34:37]
	v_mfma_f32_16x16x32_bf16 v[22:25], v[154:157], v[208:211], v[22:25]
	v_mfma_f32_16x16x32_bf16 v[18:21], v[162:165], v[208:211], v[18:21]
	v_mfma_f32_16x16x32_bf16 v[6:9], v[154:157], v[218:221], v[6:9]
	v_mfma_f32_16x16x32_bf16 v[2:5], v[162:165], v[218:221], v[2:5]
	s_barrier
	s_add_i32 s62, s62, 2
	s_add_u32 s30, s30, 0x100
	s_addc_u32 s31, s31, 0
	s_cmp_gt_u32 s62, 21
	s_cbranch_scc0 .LBB0_434
	s_and_b64 vcc, exec, s[14:15]
	s_cbranch_vccz .LBB0_437
	s_barrier

.LBB0_519:
	s_add_i32 s39, s56, 0xfffe8000
	s_and_b32 s38, s36, 0x100
	s_and_b32 s39, s39, 0x3e0000
	s_or_b32 s38, s38, s39
	s_add_u32 s57, s34, s38
	s_addc_u32 s59, s35, 0
	s_add_u32 s38, s36, 0x100
	s_addc_u32 s39, s37, 0
	s_add_i32 s41, s56, 0xffff8000
	s_and_b32 s40, s38, 0x100
	s_and_b32 s41, s41, 0x7e0000
	s_or_b32 s40, s41, s40
	s_add_u32 s40, s34, s40
	s_addc_u32 s41, s35, 0
	s_add_u32 s58, s53, s36
	s_addc_u32 s37, s54, s37
	s_add_i32 s42, s36, 0x180
	s_and_b32 s42, s42, 0x180
	s_and_b32 s43, s56, 0x7e0000
	s_or_b32 s42, s43, s42
	s_add_u32 s60, s34, s42
	s_addc_u32 s61, s35, 0
	s_cmpk_eq_i32 s36, 0x3f00
	s_cselect_b32 s43, s1, s41
	s_cselect_b32 s42, s21, s40
	s_cselect_b32 s41, s23, s37
	s_cselect_b32 s40, s22, s58
	s_cselect_b32 s37, s52, s61
	s_cselect_b32 s36, s31, s60
	s_add_i32 s60, 0, 0x10000
	v_add_u32_e32 v1, s60, v199
	ds_read_b128 v[130:133], v1
	ds_read_b128 v[134:137], v1 offset:1024
	ds_read_b128 v[138:141], v1 offset:2048
	ds_read_b128 v[142:145], v1 offset:3072
	ds_read_b128 v[146:149], v201
	ds_read_b128 v[150:153], v201 offset:1024
	ds_read_b128 v[154:157], v201 offset:2048
	ds_read_b128 v[158:161], v201 offset:3072
	s_add_u32 s58, s57, 0x10080
	s_addc_u32 s59, s59, 0
	v_lshl_add_u64 v[208:209], s[58:59], 0, v[178:179]
	s_add_i32 m0, s3, 0xc000
	ds_read_b128 v[162:165], v202
	ds_read_b128 v[166:169], v202 offset:1024
	ds_read_b128 v[170:173], v202 offset:2048
	ds_read_b128 v[174:177], v202 offset:3072
	ds_read_b128 v[186:189], v202 offset:4096
	ds_read_b128 v[190:193], v202 offset:5120
	ds_read_b128 v[194:197], v202 offset:6144
	ds_read_b128 v[204:207], v202 offset:7168
	global_load_lds_dwordx4 v[208:209], off
	v_lshl_add_u64 v[208:209], s[58:59], 0, v[182:183]
	s_add_i32 m0, s3, 0xe000
	s_nop 0
	global_load_lds_dwordx4 v[208:209], off
	s_waitcnt vmcnt(8)
	s_waitcnt lgkmcnt(0)
	s_barrier
	s_waitcnt lgkmcnt(0)
	v_mfma_f32_16x16x32_bf16 v[126:129], v[130:133], v[162:165], v[126:129]
	v_mfma_f32_16x16x32_bf16 v[122:125], v[138:141], v[162:165], v[122:125]
	v_mfma_f32_16x16x32_bf16 v[110:113], v[130:133], v[170:173], v[110:113]
	v_mfma_f32_16x16x32_bf16 v[106:109], v[138:141], v[170:173], v[106:109]
	v_mfma_f32_16x16x32_bf16 v[94:97], v[130:133], v[186:189], v[94:97]
	v_mfma_f32_16x16x32_bf16 v[90:93], v[138:141], v[186:189], v[90:93]
	v_mfma_f32_16x16x32_bf16 v[78:81], v[130:133], v[194:197], v[78:81]
	v_mfma_f32_16x16x32_bf16 v[74:77], v[138:141], v[194:197], v[74:77]
	v_mfma_f32_16x16x32_bf16 v[126:129], v[134:137], v[166:169], v[126:129]
	v_mfma_f32_16x16x32_bf16 v[122:125], v[142:145], v[166:169], v[122:125]
	v_mfma_f32_16x16x32_bf16 v[110:113], v[134:137], v[174:177], v[110:113]
	v_mfma_f32_16x16x32_bf16 v[106:109], v[142:145], v[174:177], v[106:109]
	v_mfma_f32_16x16x32_bf16 v[94:97], v[134:137], v[190:193], v[94:97]
	v_mfma_f32_16x16x32_bf16 v[90:93], v[142:145], v[190:193], v[90:93]
	v_mfma_f32_16x16x32_bf16 v[78:81], v[134:137], v[204:207], v[78:81]
	v_mfma_f32_16x16x32_bf16 v[74:77], v[142:145], v[204:207], v[74:77]
	v_mfma_f32_16x16x32_bf16 v[118:121], v[146:149], v[162:165], v[118:121]
	v_mfma_f32_16x16x32_bf16 v[114:117], v[154:157], v[162:165], v[114:117]
	v_mfma_f32_16x16x32_bf16 v[102:105], v[146:149], v[170:173], v[102:105]
	v_mfma_f32_16x16x32_bf16 v[98:101], v[154:157], v[170:173], v[98:101]
	v_mfma_f32_16x16x32_bf16 v[86:89], v[146:149], v[186:189], v[86:89]
	v_mfma_f32_16x16x32_bf16 v[82:85], v[154:157], v[186:189], v[82:85]
	v_mfma_f32_16x16x32_bf16 v[70:73], v[146:149], v[194:197], v[70:73]
	v_mfma_f32_16x16x32_bf16 v[66:69], v[154:157], v[194:197], v[66:69]
	v_mfma_f32_16x16x32_bf16 v[118:121], v[150:153], v[166:169], v[118:121]
	v_mfma_f32_16x16x32_bf16 v[114:117], v[158:161], v[166:169], v[114:117]
	v_mfma_f32_16x16x32_bf16 v[102:105], v[150:153], v[174:177], v[102:105]
	v_mfma_f32_16x16x32_bf16 v[98:101], v[158:161], v[174:177], v[98:101]
	v_mfma_f32_16x16x32_bf16 v[86:89], v[150:153], v[190:193], v[86:89]
	v_mfma_f32_16x16x32_bf16 v[82:85], v[158:161], v[190:193], v[82:85]
	v_mfma_f32_16x16x32_bf16 v[70:73], v[150:153], v[204:207], v[70:73]
	v_mfma_f32_16x16x32_bf16 v[66:69], v[158:161], v[204:207], v[66:69]
	s_barrier
	s_add_i32 s57, s60, s2
	v_lshl_add_u64 v[208:209], s[40:41], 0, v[180:181]
	s_mov_b32 m0, s57
	ds_read_b128 v[162:165], v202 offset:16384
	ds_read_b128 v[166:169], v202 offset:17408
	ds_read_b128 v[170:173], v202 offset:18432
	ds_read_b128 v[174:177], v202 offset:19456
	ds_read_b128 v[186:189], v202 offset:20480
	ds_read_b128 v[190:193], v202 offset:21504
	ds_read_b128 v[194:197], v202 offset:22528
	ds_read_b128 v[204:207], v202 offset:23552
	global_load_lds_dwordx4 v[208:209], off
	s_add_i32 m0, s57, 0x2000
	s_add_u32 s58, s40, 0x208000
	v_lshl_add_u64 v[210:211], s[40:41], 0, v[184:185]
	s_addc_u32 s59, s41, 0
	s_add_i32 s57, s49, s2
	global_load_lds_dwordx4 v[210:211], off
	v_lshl_add_u64 v[214:215], s[58:59], 0, v[180:181]
	s_mov_b32 m0, s57
	s_nop 0
	global_load_lds_dwordx4 v[214:215], off
	v_lshl_add_u64 v[214:215], s[58:59], 0, v[184:185]
	s_add_i32 m0, s57, 0x2000
	s_nop 0
	global_load_lds_dwordx4 v[214:215], off
	v_lshl_add_u64 v[214:215], s[42:43], 0, v[178:179]
	s_mov_b32 m0, s3
	s_nop 0
	global_load_lds_dwordx4 v[214:215], off
	v_lshl_add_u64 v[214:215], s[42:43], 0, v[182:183]
	s_mov_b32 m0, s33
	s_nop 0
	global_load_lds_dwordx4 v[214:215], off
	s_waitcnt vmcnt(8)
	s_waitcnt lgkmcnt(0)
	s_barrier
	s_waitcnt lgkmcnt(0)
	v_mfma_f32_16x16x32_bf16 v[62:65], v[130:133], v[162:165], v[62:65]
	v_mfma_f32_16x16x32_bf16 v[58:61], v[138:141], v[162:165], v[58:61]
	v_mfma_f32_16x16x32_bf16 v[46:49], v[130:133], v[170:173], v[46:49]
	v_mfma_f32_16x16x32_bf16 v[42:45], v[138:141], v[170:173], v[42:45]
	v_mfma_f32_16x16x32_bf16 v[30:33], v[130:133], v[186:189], v[30:33]
	v_mfma_f32_16x16x32_bf16 v[26:29], v[138:141], v[186:189], v[26:29]
	v_mfma_f32_16x16x32_bf16 v[14:17], v[130:133], v[194:197], v[14:17]
	v_mfma_f32_16x16x32_bf16 v[10:13], v[138:141], v[194:197], v[10:13]
	v_mfma_f32_16x16x32_bf16 v[62:65], v[134:137], v[166:169], v[62:65]
	v_mfma_f32_16x16x32_bf16 v[58:61], v[142:145], v[166:169], v[58:61]
	v_mfma_f32_16x16x32_bf16 v[46:49], v[134:137], v[174:177], v[46:49]
	v_mfma_f32_16x16x32_bf16 v[42:45], v[142:145], v[174:177], v[42:45]
	v_mfma_f32_16x16x32_bf16 v[30:33], v[134:137], v[190:193], v[30:33]
	v_mfma_f32_16x16x32_bf16 v[26:29], v[142:145], v[190:193], v[26:29]
	v_mfma_f32_16x16x32_bf16 v[14:17], v[134:137], v[204:207], v[14:17]
	v_mfma_f32_16x16x32_bf16 v[10:13], v[142:145], v[204:207], v[10:13]
	v_mfma_f32_16x16x32_bf16 v[54:57], v[146:149], v[162:165], v[54:57]
	v_mfma_f32_16x16x32_bf16 v[50:53], v[154:157], v[162:165], v[50:53]
	v_mfma_f32_16x16x32_bf16 v[38:41], v[146:149], v[170:173], v[38:41]
	v_mfma_f32_16x16x32_bf16 v[34:37], v[154:157], v[170:173], v[34:37]
	v_mfma_f32_16x16x32_bf16 v[22:25], v[146:149], v[186:189], v[22:25]
	v_mfma_f32_16x16x32_bf16 v[18:21], v[154:157], v[186:189], v[18:21]
	v_mfma_f32_16x16x32_bf16 v[6:9], v[146:149], v[194:197], v[6:9]
	v_mfma_f32_16x16x32_bf16 v[2:5], v[154:157], v[194:197], v[2:5]
	v_mfma_f32_16x16x32_bf16 v[54:57], v[150:153], v[166:169], v[54:57]
	v_mfma_f32_16x16x32_bf16 v[50:53], v[158:161], v[166:169], v[50:53]
	v_mfma_f32_16x16x32_bf16 v[38:41], v[150:153], v[174:177], v[38:41]
	v_mfma_f32_16x16x32_bf16 v[34:37], v[158:161], v[174:177], v[34:37]
	v_mfma_f32_16x16x32_bf16 v[22:25], v[150:153], v[190:193], v[22:25]
	v_mfma_f32_16x16x32_bf16 v[18:21], v[158:161], v[190:193], v[18:21]
	v_mfma_f32_16x16x32_bf16 v[6:9], v[150:153], v[204:207], v[6:9]
	v_mfma_f32_16x16x32_bf16 v[2:5], v[158:161], v[204:207], v[2:5]
	s_barrier
	s_add_i32 s57, 0, 0x18000
	v_add_u32_e32 v1, s57, v199
	s_add_i32 s58, 0, 0x1c000
	ds_read_b128 v[130:133], v1
	ds_read_b128 v[134:137], v1 offset:1024
	ds_read_b128 v[138:141], v1 offset:2048
	ds_read_b128 v[142:145], v1 offset:3072
	v_add_u32_e32 v1, s58, v199
	ds_read_b128 v[146:149], v1
	ds_read_b128 v[150:153], v1 offset:1024
	ds_read_b128 v[154:157], v1 offset:2048
	ds_read_b128 v[158:161], v1 offset:3072
	s_add_u32 s42, s42, 0x10000
	s_addc_u32 s43, s43, 0
	s_mov_b32 m0, s44
	v_lshl_add_u64 v[214:215], s[42:43], 0, v[178:179]
	ds_read_b128 v[162:165], v202 offset:32768
	ds_read_b128 v[166:169], v202 offset:33792
	ds_read_b128 v[170:173], v202 offset:34816
	ds_read_b128 v[174:177], v202 offset:35840
	ds_read_b128 v[186:189], v202 offset:36864
	ds_read_b128 v[190:193], v202 offset:37888
	ds_read_b128 v[194:197], v202 offset:38912
	ds_read_b128 v[204:207], v202 offset:39936
	global_load_lds_dwordx4 v[214:215], off
	v_lshl_add_u64 v[214:215], s[42:43], 0, v[182:183]
	s_mov_b32 m0, s45
	s_nop 0
	global_load_lds_dwordx4 v[214:215], off
	s_waitcnt vmcnt(8)
	s_waitcnt lgkmcnt(0)
	s_barrier
	s_waitcnt lgkmcnt(0)
	v_mfma_f32_16x16x32_bf16 v[126:129], v[130:133], v[162:165], v[126:129]
	v_mfma_f32_16x16x32_bf16 v[122:125], v[138:141], v[162:165], v[122:125]
	v_mfma_f32_16x16x32_bf16 v[110:113], v[130:133], v[170:173], v[110:113]
	v_mfma_f32_16x16x32_bf16 v[106:109], v[138:141], v[170:173], v[106:109]
	v_mfma_f32_16x16x32_bf16 v[94:97], v[130:133], v[186:189], v[94:97]
	v_mfma_f32_16x16x32_bf16 v[90:93], v[138:141], v[186:189], v[90:93]
	v_mfma_f32_16x16x32_bf16 v[78:81], v[130:133], v[194:197], v[78:81]
	v_mfma_f32_16x16x32_bf16 v[74:77], v[138:141], v[194:197], v[74:77]
	v_mfma_f32_16x16x32_bf16 v[126:129], v[134:137], v[166:169], v[126:129]
	v_mfma_f32_16x16x32_bf16 v[122:125], v[142:145], v[166:169], v[122:125]
	v_mfma_f32_16x16x32_bf16 v[110:113], v[134:137], v[174:177], v[110:113]
	v_mfma_f32_16x16x32_bf16 v[106:109], v[142:145], v[174:177], v[106:109]
	v_mfma_f32_16x16x32_bf16 v[94:97], v[134:137], v[190:193], v[94:97]
	v_mfma_f32_16x16x32_bf16 v[90:93], v[142:145], v[190:193], v[90:93]
	v_mfma_f32_16x16x32_bf16 v[78:81], v[134:137], v[204:207], v[78:81]
	v_mfma_f32_16x16x32_bf16 v[74:77], v[142:145], v[204:207], v[74:77]
	v_mfma_f32_16x16x32_bf16 v[118:121], v[146:149], v[162:165], v[118:121]
	v_mfma_f32_16x16x32_bf16 v[114:117], v[154:157], v[162:165], v[114:117]
	v_mfma_f32_16x16x32_bf16 v[102:105], v[146:149], v[170:173], v[102:105]
	v_mfma_f32_16x16x32_bf16 v[98:101], v[154:157], v[170:173], v[98:101]
	v_mfma_f32_16x16x32_bf16 v[86:89], v[146:149], v[186:189], v[86:89]
	v_mfma_f32_16x16x32_bf16 v[82:85], v[154:157], v[186:189], v[82:85]
	v_mfma_f32_16x16x32_bf16 v[70:73], v[146:149], v[194:197], v[70:73]
	v_mfma_f32_16x16x32_bf16 v[66:69], v[154:157], v[194:197], v[66:69]
	v_mfma_f32_16x16x32_bf16 v[118:121], v[150:153], v[166:169], v[118:121]
	v_mfma_f32_16x16x32_bf16 v[114:117], v[158:161], v[166:169], v[114:117]
	v_mfma_f32_16x16x32_bf16 v[102:105], v[150:153], v[174:177], v[102:105]
	v_mfma_f32_16x16x32_bf16 v[98:101], v[158:161], v[174:177], v[98:101]
	v_mfma_f32_16x16x32_bf16 v[86:89], v[150:153], v[190:193], v[86:89]
	v_mfma_f32_16x16x32_bf16 v[82:85], v[158:161], v[190:193], v[82:85]
	v_mfma_f32_16x16x32_bf16 v[70:73], v[150:153], v[204:207], v[70:73]
	v_mfma_f32_16x16x32_bf16 v[66:69], v[158:161], v[204:207], v[66:69]
	s_barrier
	s_add_i32 s42, s57, s2
	v_lshl_add_u64 v[208:209], v[208:209], 0, s[16:17]
	s_mov_b32 m0, s42
	ds_read_b128 v[162:165], v202 offset:49152
	ds_read_b128 v[166:169], v202 offset:50176
	ds_read_b128 v[170:173], v202 offset:51200
	ds_read_b128 v[174:177], v202 offset:52224
	ds_read_b128 v[186:189], v202 offset:53248
	ds_read_b128 v[190:193], v202 offset:54272
	ds_read_b128 v[194:197], v202 offset:55296
	ds_read_b128 v[204:207], v202 offset:56320
	global_load_lds_dwordx4 v[208:209], off
	s_add_i32 m0, s42, 0x2000
	s_add_u32 s40, s40, 0x208080
	v_lshl_add_u64 v[208:209], v[210:211], 0, s[16:17]
	s_addc_u32 s41, s41, 0
	s_add_i32 s42, s58, s2
	global_load_lds_dwordx4 v[208:209], off
	v_lshl_add_u64 v[208:209], s[40:41], 0, v[180:181]
	s_mov_b32 m0, s42
	s_nop 0
	global_load_lds_dwordx4 v[208:209], off
	v_lshl_add_u64 v[208:209], s[40:41], 0, v[184:185]
	s_add_i32 m0, s42, 0x2000
	s_nop 0
	global_load_lds_dwordx4 v[208:209], off
	v_lshl_add_u64 v[208:209], s[36:37], 0, v[178:179]
	s_mov_b32 m0, s47
	s_nop 0
	global_load_lds_dwordx4 v[208:209], off
	v_lshl_add_u64 v[208:209], s[36:37], 0, v[182:183]
	s_mov_b32 m0, s48
	s_nop 0
	global_load_lds_dwordx4 v[208:209], off
	s_waitcnt vmcnt(8)
	s_waitcnt lgkmcnt(0)
	s_barrier
	s_waitcnt lgkmcnt(0)
	v_mfma_f32_16x16x32_bf16 v[62:65], v[130:133], v[162:165], v[62:65]
	v_mfma_f32_16x16x32_bf16 v[58:61], v[138:141], v[162:165], v[58:61]
	v_mfma_f32_16x16x32_bf16 v[46:49], v[130:133], v[170:173], v[46:49]
	v_mfma_f32_16x16x32_bf16 v[42:45], v[138:141], v[170:173], v[42:45]
	v_mfma_f32_16x16x32_bf16 v[30:33], v[130:133], v[186:189], v[30:33]
	v_mfma_f32_16x16x32_bf16 v[26:29], v[138:141], v[186:189], v[26:29]
	v_mfma_f32_16x16x32_bf16 v[14:17], v[130:133], v[194:197], v[14:17]
	v_mfma_f32_16x16x32_bf16 v[10:13], v[138:141], v[194:197], v[10:13]
	v_mfma_f32_16x16x32_bf16 v[62:65], v[134:137], v[166:169], v[62:65]
	v_mfma_f32_16x16x32_bf16 v[58:61], v[142:145], v[166:169], v[58:61]
	v_mfma_f32_16x16x32_bf16 v[46:49], v[134:137], v[174:177], v[46:49]
	v_mfma_f32_16x16x32_bf16 v[42:45], v[142:145], v[174:177], v[42:45]
	v_mfma_f32_16x16x32_bf16 v[30:33], v[134:137], v[190:193], v[30:33]
	v_mfma_f32_16x16x32_bf16 v[26:29], v[142:145], v[190:193], v[26:29]
	v_mfma_f32_16x16x32_bf16 v[14:17], v[134:137], v[204:207], v[14:17]
	v_mfma_f32_16x16x32_bf16 v[10:13], v[142:145], v[204:207], v[10:13]
	v_mfma_f32_16x16x32_bf16 v[54:57], v[146:149], v[162:165], v[54:57]
	v_mfma_f32_16x16x32_bf16 v[50:53], v[154:157], v[162:165], v[50:53]
	v_mfma_f32_16x16x32_bf16 v[38:41], v[146:149], v[170:173], v[38:41]
	v_mfma_f32_16x16x32_bf16 v[34:37], v[154:157], v[170:173], v[34:37]
	v_mfma_f32_16x16x32_bf16 v[22:25], v[146:149], v[186:189], v[22:25]
	v_mfma_f32_16x16x32_bf16 v[18:21], v[154:157], v[186:189], v[18:21]
	v_mfma_f32_16x16x32_bf16 v[6:9], v[146:149], v[194:197], v[6:9]
	v_mfma_f32_16x16x32_bf16 v[2:5], v[154:157], v[194:197], v[2:5]
	v_mfma_f32_16x16x32_bf16 v[54:57], v[150:153], v[166:169], v[54:57]
	v_mfma_f32_16x16x32_bf16 v[50:53], v[158:161], v[166:169], v[50:53]
	v_mfma_f32_16x16x32_bf16 v[38:41], v[150:153], v[174:177], v[38:41]
	v_mfma_f32_16x16x32_bf16 v[34:37], v[158:161], v[174:177], v[34:37]
	v_mfma_f32_16x16x32_bf16 v[22:25], v[150:153], v[190:193], v[22:25]
	v_mfma_f32_16x16x32_bf16 v[18:21], v[158:161], v[190:193], v[18:21]
	v_mfma_f32_16x16x32_bf16 v[6:9], v[150:153], v[204:207], v[6:9]
	v_mfma_f32_16x16x32_bf16 v[2:5], v[158:161], v[204:207], v[2:5]
	s_barrier
	s_add_i32 s55, s55, 2
	s_add_i32 s56, s56, 0x10000
	s_cmpk_gt_u32 s55, 0x7d
	s_mov_b64 s[36:37], s[38:39]
	s_cbranch_scc0 .LBB0_519
	s_and_b64 vcc, exec, s[18:19]
	s_cbranch_vccz .LBB0_522
	s_barrier

.LBB0_612:
	ds_read_b128 v[166:169], v152
	ds_read_b128 v[170:173], v152 offset:1024
	ds_read_b128 v[174:177], v152 offset:2048
	ds_read_b128 v[178:181], v152 offset:3072
	ds_read_b128 v[182:185], v153
	ds_read_b128 v[186:189], v153 offset:1024
	ds_read_b128 v[190:193], v153 offset:2048
	ds_read_b128 v[194:197], v153 offset:3072
	s_add_u32 s26, s4, s22
	s_addc_u32 s27, s5, s23
	s_add_u32 s30, s26, 0x100
	s_addc_u32 s31, s27, 0
	s_add_u32 s28, s52, s22
	s_addc_u32 s29, s53, s23
	s_add_u32 s26, s26, 0x180
	s_addc_u32 s27, s27, 0
	s_cmpk_eq_i32 s22, 0x1f00
	s_cselect_b32 s27, s51, s27
	s_cselect_b32 s26, s50, s26
	s_cselect_b32 s29, s21, s29
	s_cselect_b32 s28, s20, s28
	s_cselect_b32 s31, s19, s31
	s_cselect_b32 s30, s18, s30
	s_mov_b32 m0, s37
	v_lshl_add_u64 v[210:211], v[148:149], 0, s[22:23]
	ds_read_b128 v[198:201], v154
	ds_read_b128 v[202:205], v154 offset:1024
	ds_read_b128 v[206:209], v154 offset:2048
	ds_read_b128 v[214:217], v154 offset:3072
	ds_read_b128 v[218:221], v154 offset:4096
	ds_read_b128 v[222:225], v154 offset:5120
	ds_read_b128 v[226:229], v154 offset:6144
	ds_read_b128 v[230:233], v154 offset:7168
	global_load_lds_dwordx4 v[210:211], off
	v_lshl_add_u64 v[210:211], v[150:151], 0, s[22:23]
	s_mov_b32 m0, s38
	s_nop 0
	global_load_lds_dwordx4 v[210:211], off
	s_waitcnt vmcnt(8)
	s_waitcnt lgkmcnt(0)
	s_barrier
	s_waitcnt lgkmcnt(0)
	v_mfma_f32_16x16x32_bf16 v[126:129], v[166:169], v[198:201], v[126:129]
	v_mfma_f32_16x16x32_bf16 v[122:125], v[174:177], v[198:201], v[122:125]
	v_mfma_f32_16x16x32_bf16 v[110:113], v[166:169], v[206:209], v[110:113]
	v_mfma_f32_16x16x32_bf16 v[106:109], v[174:177], v[206:209], v[106:109]
	v_mfma_f32_16x16x32_bf16 v[94:97], v[166:169], v[218:221], v[94:97]
	v_mfma_f32_16x16x32_bf16 v[90:93], v[174:177], v[218:221], v[90:93]
	v_mfma_f32_16x16x32_bf16 v[78:81], v[166:169], v[226:229], v[78:81]
	v_mfma_f32_16x16x32_bf16 v[74:77], v[174:177], v[226:229], v[74:77]
	v_mfma_f32_16x16x32_bf16 v[126:129], v[170:173], v[202:205], v[126:129]
	v_mfma_f32_16x16x32_bf16 v[122:125], v[178:181], v[202:205], v[122:125]
	v_mfma_f32_16x16x32_bf16 v[110:113], v[170:173], v[214:217], v[110:113]
	v_mfma_f32_16x16x32_bf16 v[106:109], v[178:181], v[214:217], v[106:109]
	v_mfma_f32_16x16x32_bf16 v[94:97], v[170:173], v[222:225], v[94:97]
	v_mfma_f32_16x16x32_bf16 v[90:93], v[178:181], v[222:225], v[90:93]
	v_mfma_f32_16x16x32_bf16 v[78:81], v[170:173], v[230:233], v[78:81]
	v_mfma_f32_16x16x32_bf16 v[74:77], v[178:181], v[230:233], v[74:77]
	v_mfma_f32_16x16x32_bf16 v[118:121], v[182:185], v[198:201], v[118:121]
	v_mfma_f32_16x16x32_bf16 v[114:117], v[190:193], v[198:201], v[114:117]
	v_mfma_f32_16x16x32_bf16 v[102:105], v[182:185], v[206:209], v[102:105]
	v_mfma_f32_16x16x32_bf16 v[98:101], v[190:193], v[206:209], v[98:101]
	v_mfma_f32_16x16x32_bf16 v[86:89], v[182:185], v[218:221], v[86:89]
	v_mfma_f32_16x16x32_bf16 v[82:85], v[190:193], v[218:221], v[82:85]
	v_mfma_f32_16x16x32_bf16 v[70:73], v[182:185], v[226:229], v[70:73]
	v_mfma_f32_16x16x32_bf16 v[66:69], v[190:193], v[226:229], v[66:69]
	v_mfma_f32_16x16x32_bf16 v[118:121], v[186:189], v[202:205], v[118:121]
	v_mfma_f32_16x16x32_bf16 v[114:117], v[194:197], v[202:205], v[114:117]
	v_mfma_f32_16x16x32_bf16 v[102:105], v[186:189], v[214:217], v[102:105]
	v_mfma_f32_16x16x32_bf16 v[98:101], v[194:197], v[214:217], v[98:101]
	v_mfma_f32_16x16x32_bf16 v[86:89], v[186:189], v[222:225], v[86:89]
	v_mfma_f32_16x16x32_bf16 v[82:85], v[194:197], v[222:225], v[82:85]
	v_mfma_f32_16x16x32_bf16 v[70:73], v[186:189], v[230:233], v[70:73]
	v_mfma_f32_16x16x32_bf16 v[66:69], v[194:197], v[230:233], v[66:69]
	s_barrier
	s_mov_b32 m0, s39
	v_lshl_add_u64 v[210:211], s[28:29], 0, v[132:133]
	s_add_u32 s56, s28, 0x108000
	ds_read_b128 v[198:201], v154 offset:16384
	ds_read_b128 v[202:205], v154 offset:17408
	ds_read_b128 v[206:209], v154 offset:18432
	ds_read_b128 v[214:217], v154 offset:19456
	ds_read_b128 v[218:221], v154 offset:20480
	ds_read_b128 v[222:225], v154 offset:21504
	ds_read_b128 v[226:229], v154 offset:22528
	ds_read_b128 v[230:233], v154 offset:23552
	global_load_lds_dwordx4 v[210:211], off
	v_lshl_add_u64 v[234:235], s[28:29], 0, v[136:137]
	s_mov_b32 m0, s40
	s_addc_u32 s57, s29, 0
	global_load_lds_dwordx4 v[234:235], off
	v_lshl_add_u64 v[236:237], s[56:57], 0, v[132:133]
	s_mov_b32 m0, s41
	s_nop 0
	global_load_lds_dwordx4 v[236:237], off
	v_lshl_add_u64 v[236:237], s[56:57], 0, v[136:137]
	s_mov_b32 m0, s42
	s_nop 0
	global_load_lds_dwordx4 v[236:237], off
	v_lshl_add_u64 v[236:237], s[30:31], 0, v[130:131]
	s_mov_b32 m0, s2
	s_nop 0
	global_load_lds_dwordx4 v[236:237], off
	v_lshl_add_u64 v[236:237], s[30:31], 0, v[134:135]
	s_mov_b32 m0, s3
	s_nop 0
	global_load_lds_dwordx4 v[236:237], off
	s_waitcnt vmcnt(8)
	s_waitcnt lgkmcnt(0)
	s_barrier
	s_waitcnt lgkmcnt(0)
	v_mfma_f32_16x16x32_bf16 v[62:65], v[166:169], v[198:201], v[62:65]
	v_mfma_f32_16x16x32_bf16 v[58:61], v[174:177], v[198:201], v[58:61]
	v_mfma_f32_16x16x32_bf16 v[46:49], v[166:169], v[206:209], v[46:49]
	v_mfma_f32_16x16x32_bf16 v[42:45], v[174:177], v[206:209], v[42:45]
	v_mfma_f32_16x16x32_bf16 v[30:33], v[166:169], v[218:221], v[30:33]
	v_mfma_f32_16x16x32_bf16 v[26:29], v[174:177], v[218:221], v[26:29]
	v_mfma_f32_16x16x32_bf16 v[14:17], v[166:169], v[226:229], v[14:17]
	v_mfma_f32_16x16x32_bf16 v[10:13], v[174:177], v[226:229], v[10:13]
	v_mfma_f32_16x16x32_bf16 v[62:65], v[170:173], v[202:205], v[62:65]
	v_mfma_f32_16x16x32_bf16 v[58:61], v[178:181], v[202:205], v[58:61]
	v_mfma_f32_16x16x32_bf16 v[46:49], v[170:173], v[214:217], v[46:49]
	v_mfma_f32_16x16x32_bf16 v[42:45], v[178:181], v[214:217], v[42:45]
	v_mfma_f32_16x16x32_bf16 v[30:33], v[170:173], v[222:225], v[30:33]
	v_mfma_f32_16x16x32_bf16 v[26:29], v[178:181], v[222:225], v[26:29]
	v_mfma_f32_16x16x32_bf16 v[14:17], v[170:173], v[230:233], v[14:17]
	v_mfma_f32_16x16x32_bf16 v[10:13], v[178:181], v[230:233], v[10:13]
	v_mfma_f32_16x16x32_bf16 v[54:57], v[182:185], v[198:201], v[54:57]
	v_mfma_f32_16x16x32_bf16 v[50:53], v[190:193], v[198:201], v[50:53]
	v_mfma_f32_16x16x32_bf16 v[38:41], v[182:185], v[206:209], v[38:41]
	v_mfma_f32_16x16x32_bf16 v[34:37], v[190:193], v[206:209], v[34:37]
	v_mfma_f32_16x16x32_bf16 v[22:25], v[182:185], v[218:221], v[22:25]
	v_mfma_f32_16x16x32_bf16 v[18:21], v[190:193], v[218:221], v[18:21]
	v_mfma_f32_16x16x32_bf16 v[6:9], v[182:185], v[226:229], v[6:9]
	v_mfma_f32_16x16x32_bf16 v[2:5], v[190:193], v[226:229], v[2:5]
	v_mfma_f32_16x16x32_bf16 v[54:57], v[186:189], v[202:205], v[54:57]
	v_mfma_f32_16x16x32_bf16 v[50:53], v[194:197], v[202:205], v[50:53]
	v_mfma_f32_16x16x32_bf16 v[38:41], v[186:189], v[214:217], v[38:41]
	v_mfma_f32_16x16x32_bf16 v[34:37], v[194:197], v[214:217], v[34:37]
	v_mfma_f32_16x16x32_bf16 v[22:25], v[186:189], v[222:225], v[22:25]
	v_mfma_f32_16x16x32_bf16 v[18:21], v[194:197], v[222:225], v[18:21]
	v_mfma_f32_16x16x32_bf16 v[6:9], v[186:189], v[230:233], v[6:9]
	v_mfma_f32_16x16x32_bf16 v[2:5], v[194:197], v[230:233], v[2:5]
	s_barrier
	ds_read_b128 v[166:169], v156
	ds_read_b128 v[170:173], v156 offset:1024
	ds_read_b128 v[174:177], v156 offset:2048
	ds_read_b128 v[178:181], v156 offset:3072
	ds_read_b128 v[182:185], v157
	ds_read_b128 v[186:189], v157 offset:1024
	ds_read_b128 v[190:193], v157 offset:2048
	ds_read_b128 v[194:197], v157 offset:3072
	s_add_u32 s30, s30, 0x108000
	s_addc_u32 s31, s31, 0
	s_mov_b32 m0, s33
	v_lshl_add_u64 v[236:237], s[30:31], 0, v[130:131]
	ds_read_b128 v[198:201], v154 offset:32768
	ds_read_b128 v[202:205], v154 offset:33792
	ds_read_b128 v[206:209], v154 offset:34816
	ds_read_b128 v[214:217], v154 offset:35840
	ds_read_b128 v[218:221], v154 offset:36864
	ds_read_b128 v[222:225], v154 offset:37888
	ds_read_b128 v[226:229], v154 offset:38912
	ds_read_b128 v[230:233], v154 offset:39936
	global_load_lds_dwordx4 v[236:237], off
	v_lshl_add_u64 v[236:237], s[30:31], 0, v[134:135]
	s_mov_b32 m0, s34
	s_nop 0
	global_load_lds_dwordx4 v[236:237], off
	s_waitcnt vmcnt(8)
	s_waitcnt lgkmcnt(0)
	s_barrier
	s_waitcnt lgkmcnt(0)
	v_mfma_f32_16x16x32_bf16 v[126:129], v[166:169], v[198:201], v[126:129]
	v_mfma_f32_16x16x32_bf16 v[122:125], v[174:177], v[198:201], v[122:125]
	v_mfma_f32_16x16x32_bf16 v[110:113], v[166:169], v[206:209], v[110:113]
	v_mfma_f32_16x16x32_bf16 v[106:109], v[174:177], v[206:209], v[106:109]
	v_mfma_f32_16x16x32_bf16 v[94:97], v[166:169], v[218:221], v[94:97]
	v_mfma_f32_16x16x32_bf16 v[90:93], v[174:177], v[218:221], v[90:93]
	v_mfma_f32_16x16x32_bf16 v[78:81], v[166:169], v[226:229], v[78:81]
	v_mfma_f32_16x16x32_bf16 v[74:77], v[174:177], v[226:229], v[74:77]
	v_mfma_f32_16x16x32_bf16 v[126:129], v[170:173], v[202:205], v[126:129]
	v_mfma_f32_16x16x32_bf16 v[122:125], v[178:181], v[202:205], v[122:125]
	v_mfma_f32_16x16x32_bf16 v[110:113], v[170:173], v[214:217], v[110:113]
	v_mfma_f32_16x16x32_bf16 v[106:109], v[178:181], v[214:217], v[106:109]
	v_mfma_f32_16x16x32_bf16 v[94:97], v[170:173], v[222:225], v[94:97]
	v_mfma_f32_16x16x32_bf16 v[90:93], v[178:181], v[222:225], v[90:93]
	v_mfma_f32_16x16x32_bf16 v[78:81], v[170:173], v[230:233], v[78:81]
	v_mfma_f32_16x16x32_bf16 v[74:77], v[178:181], v[230:233], v[74:77]
	v_mfma_f32_16x16x32_bf16 v[118:121], v[182:185], v[198:201], v[118:121]
	v_mfma_f32_16x16x32_bf16 v[114:117], v[190:193], v[198:201], v[114:117]
	v_mfma_f32_16x16x32_bf16 v[102:105], v[182:185], v[206:209], v[102:105]
	v_mfma_f32_16x16x32_bf16 v[98:101], v[190:193], v[206:209], v[98:101]
	v_mfma_f32_16x16x32_bf16 v[86:89], v[182:185], v[218:221], v[86:89]
	v_mfma_f32_16x16x32_bf16 v[82:85], v[190:193], v[218:221], v[82:85]
	v_mfma_f32_16x16x32_bf16 v[70:73], v[182:185], v[226:229], v[70:73]
	v_mfma_f32_16x16x32_bf16 v[66:69], v[190:193], v[226:229], v[66:69]
	v_mfma_f32_16x16x32_bf16 v[118:121], v[186:189], v[202:205], v[118:121]
	v_mfma_f32_16x16x32_bf16 v[114:117], v[194:197], v[202:205], v[114:117]
	v_mfma_f32_16x16x32_bf16 v[102:105], v[186:189], v[214:217], v[102:105]
	v_mfma_f32_16x16x32_bf16 v[98:101], v[194:197], v[214:217], v[98:101]
	v_mfma_f32_16x16x32_bf16 v[86:89], v[186:189], v[222:225], v[86:89]
	v_mfma_f32_16x16x32_bf16 v[82:85], v[194:197], v[222:225], v[82:85]
	v_mfma_f32_16x16x32_bf16 v[70:73], v[186:189], v[230:233], v[70:73]
	v_mfma_f32_16x16x32_bf16 v[66:69], v[194:197], v[230:233], v[66:69]
	s_barrier
	s_mov_b32 m0, s43
	v_lshl_add_u64 v[210:211], v[210:211], 0, s[14:15]
	s_add_u32 s28, s28, 0x108080
	ds_read_b128 v[198:201], v154 offset:49152
	ds_read_b128 v[202:205], v154 offset:50176
	ds_read_b128 v[206:209], v154 offset:51200
	ds_read_b128 v[214:217], v154 offset:52224
	ds_read_b128 v[218:221], v154 offset:53248
	ds_read_b128 v[222:225], v154 offset:54272
	ds_read_b128 v[226:229], v154 offset:55296
	ds_read_b128 v[230:233], v154 offset:56320
	global_load_lds_dwordx4 v[210:211], off
	v_lshl_add_u64 v[210:211], v[234:235], 0, s[14:15]
	s_mov_b32 m0, s44
	s_addc_u32 s29, s29, 0
	global_load_lds_dwordx4 v[210:211], off
	v_lshl_add_u64 v[210:211], s[28:29], 0, v[132:133]
	s_mov_b32 m0, s45
	s_nop 0
	global_load_lds_dwordx4 v[210:211], off
	v_lshl_add_u64 v[210:211], s[28:29], 0, v[136:137]
	s_mov_b32 m0, s46
	s_nop 0
	global_load_lds_dwordx4 v[210:211], off
	v_lshl_add_u64 v[210:211], s[26:27], 0, v[130:131]
	s_mov_b32 m0, s35
	s_nop 0
	global_load_lds_dwordx4 v[210:211], off
	v_lshl_add_u64 v[210:211], s[26:27], 0, v[134:135]
	s_mov_b32 m0, s36
	s_nop 0
	global_load_lds_dwordx4 v[210:211], off
	s_waitcnt vmcnt(8)
	s_waitcnt lgkmcnt(0)
	s_barrier
	s_waitcnt lgkmcnt(0)
	v_mfma_f32_16x16x32_bf16 v[62:65], v[166:169], v[198:201], v[62:65]
	v_mfma_f32_16x16x32_bf16 v[58:61], v[174:177], v[198:201], v[58:61]
	v_mfma_f32_16x16x32_bf16 v[46:49], v[166:169], v[206:209], v[46:49]
	v_mfma_f32_16x16x32_bf16 v[42:45], v[174:177], v[206:209], v[42:45]
	v_mfma_f32_16x16x32_bf16 v[30:33], v[166:169], v[218:221], v[30:33]
	v_mfma_f32_16x16x32_bf16 v[26:29], v[174:177], v[218:221], v[26:29]
	v_mfma_f32_16x16x32_bf16 v[14:17], v[166:169], v[226:229], v[14:17]
	v_mfma_f32_16x16x32_bf16 v[10:13], v[174:177], v[226:229], v[10:13]
	v_mfma_f32_16x16x32_bf16 v[62:65], v[170:173], v[202:205], v[62:65]
	v_mfma_f32_16x16x32_bf16 v[58:61], v[178:181], v[202:205], v[58:61]
	v_mfma_f32_16x16x32_bf16 v[46:49], v[170:173], v[214:217], v[46:49]
	v_mfma_f32_16x16x32_bf16 v[42:45], v[178:181], v[214:217], v[42:45]
	v_mfma_f32_16x16x32_bf16 v[30:33], v[170:173], v[222:225], v[30:33]
	v_mfma_f32_16x16x32_bf16 v[26:29], v[178:181], v[222:225], v[26:29]
	v_mfma_f32_16x16x32_bf16 v[14:17], v[170:173], v[230:233], v[14:17]
	v_mfma_f32_16x16x32_bf16 v[10:13], v[178:181], v[230:233], v[10:13]
	v_mfma_f32_16x16x32_bf16 v[54:57], v[182:185], v[198:201], v[54:57]
	v_mfma_f32_16x16x32_bf16 v[50:53], v[190:193], v[198:201], v[50:53]
	v_mfma_f32_16x16x32_bf16 v[38:41], v[182:185], v[206:209], v[38:41]
	v_mfma_f32_16x16x32_bf16 v[34:37], v[190:193], v[206:209], v[34:37]
	v_mfma_f32_16x16x32_bf16 v[22:25], v[182:185], v[218:221], v[22:25]
	v_mfma_f32_16x16x32_bf16 v[18:21], v[190:193], v[218:221], v[18:21]
	v_mfma_f32_16x16x32_bf16 v[6:9], v[182:185], v[226:229], v[6:9]
	v_mfma_f32_16x16x32_bf16 v[2:5], v[190:193], v[226:229], v[2:5]
	v_mfma_f32_16x16x32_bf16 v[54:57], v[186:189], v[202:205], v[54:57]
	v_mfma_f32_16x16x32_bf16 v[50:53], v[194:197], v[202:205], v[50:53]
	v_mfma_f32_16x16x32_bf16 v[38:41], v[186:189], v[214:217], v[38:41]
	v_mfma_f32_16x16x32_bf16 v[34:37], v[194:197], v[214:217], v[34:37]
	v_mfma_f32_16x16x32_bf16 v[22:25], v[186:189], v[222:225], v[22:25]
	v_mfma_f32_16x16x32_bf16 v[18:21], v[194:197], v[222:225], v[18:21]
	v_mfma_f32_16x16x32_bf16 v[6:9], v[186:189], v[230:233], v[6:9]
	v_mfma_f32_16x16x32_bf16 v[2:5], v[194:197], v[230:233], v[2:5]
	s_barrier
	s_add_i32 s54, s54, 2
	s_add_u32 s22, s22, 0x100
	s_addc_u32 s23, s23, 0
	s_cmp_gt_u32 s54, 61
	s_cbranch_scc0 .LBB0_612
	s_and_b64 vcc, exec, s[16:17]
	s_cbranch_vccz .LBB0_615
	s_barrier

.LBB0_844:
	s_add_i32 s35, s52, 0xfffe8000
	s_and_b32 s34, s30, 0x100
	s_and_b32 s35, s35, 0x3e0000
	s_or_b32 s34, s34, s35
	s_add_u32 s53, s28, s34
	s_addc_u32 s55, s29, 0
	s_add_u32 s34, s30, 0x100
	s_addc_u32 s35, s31, 0
	s_add_i32 s37, s52, 0xffff8000
	s_and_b32 s36, s34, 0x100
	s_and_b32 s37, s37, 0x7e0000
	s_or_b32 s36, s37, s36
	s_add_u32 s36, s28, s36
	s_addc_u32 s37, s29, 0
	s_add_u32 s54, s49, s30
	s_addc_u32 s31, s50, s31
	s_add_i32 s38, s30, 0x180
	s_and_b32 s38, s38, 0x180
	s_and_b32 s39, s52, 0x7e0000
	s_or_b32 s38, s39, s38
	s_add_u32 s56, s28, s38
	s_addc_u32 s57, s29, 0
	s_cmpk_eq_i32 s30, 0x3f00
	s_cselect_b32 s39, s1, s37
	s_cselect_b32 s38, s21, s36
	s_cselect_b32 s37, s23, s31
	s_cselect_b32 s36, s22, s54
	s_cselect_b32 s31, s48, s57
	s_cselect_b32 s30, s27, s56
	s_add_i32 s56, 0, 0x10000
	v_add_u32_e32 v124, s56, v211
	ds_read_b128 v[104:107], v124
	ds_read_b128 v[108:111], v124 offset:1024
	ds_read_b128 v[120:123], v124 offset:2048
	ds_read_b128 v[124:127], v124 offset:3072
	ds_read_b128 v[144:147], v214
	ds_read_b128 v[148:151], v214 offset:1024
	ds_read_b128 v[152:155], v214 offset:2048
	ds_read_b128 v[156:159], v214 offset:3072
	s_add_u32 s54, s53, 0x10080
	s_addc_u32 s55, s55, 0
	v_lshl_add_u64 v[200:201], s[54:55], 0, v[184:185]
	s_add_i32 m0, s3, 0xc000
	ds_read_b128 v[160:163], v215
	ds_read_b128 v[164:167], v215 offset:1024
	ds_read_b128 v[168:171], v215 offset:2048
	ds_read_b128 v[172:175], v215 offset:3072
	ds_read_b128 v[176:179], v215 offset:4096
	ds_read_b128 v[180:183], v215 offset:5120
	ds_read_b128 v[192:195], v215 offset:6144
	ds_read_b128 v[196:199], v215 offset:7168
	global_load_lds_dwordx4 v[200:201], off
	v_lshl_add_u64 v[200:201], s[54:55], 0, v[188:189]
	s_add_i32 m0, s3, 0xe000
	s_nop 0
	global_load_lds_dwordx4 v[200:201], off
	s_waitcnt vmcnt(8)
	s_waitcnt lgkmcnt(0)
	s_barrier
	s_waitcnt lgkmcnt(0)
	v_mfma_f32_16x16x32_bf16 v[140:143], v[104:107], v[160:163], v[140:143]
	v_mfma_f32_16x16x32_bf16 v[136:139], v[120:123], v[160:163], v[136:139]
	v_mfma_f32_16x16x32_bf16 v[116:119], v[104:107], v[168:171], v[116:119]
	v_mfma_f32_16x16x32_bf16 v[112:115], v[120:123], v[168:171], v[112:115]
	v_mfma_f32_16x16x32_bf16 v[92:95], v[104:107], v[176:179], v[92:95]
	v_mfma_f32_16x16x32_bf16 v[88:91], v[120:123], v[176:179], v[88:91]
	v_mfma_f32_16x16x32_bf16 v[76:79], v[104:107], v[192:195], v[76:79]
	v_mfma_f32_16x16x32_bf16 v[72:75], v[120:123], v[192:195], v[72:75]
	v_mfma_f32_16x16x32_bf16 v[140:143], v[108:111], v[164:167], v[140:143]
	v_mfma_f32_16x16x32_bf16 v[136:139], v[124:127], v[164:167], v[136:139]
	v_mfma_f32_16x16x32_bf16 v[116:119], v[108:111], v[172:175], v[116:119]
	v_mfma_f32_16x16x32_bf16 v[112:115], v[124:127], v[172:175], v[112:115]
	v_mfma_f32_16x16x32_bf16 v[92:95], v[108:111], v[180:183], v[92:95]
	v_mfma_f32_16x16x32_bf16 v[88:91], v[124:127], v[180:183], v[88:91]
	v_mfma_f32_16x16x32_bf16 v[76:79], v[108:111], v[196:199], v[76:79]
	v_mfma_f32_16x16x32_bf16 v[72:75], v[124:127], v[196:199], v[72:75]
	v_mfma_f32_16x16x32_bf16 v[132:135], v[144:147], v[160:163], v[132:135]
	v_mfma_f32_16x16x32_bf16 v[128:131], v[152:155], v[160:163], v[128:131]
	v_mfma_f32_16x16x32_bf16 v[100:103], v[144:147], v[168:171], v[100:103]
	v_mfma_f32_16x16x32_bf16 v[96:99], v[152:155], v[168:171], v[96:99]
	v_mfma_f32_16x16x32_bf16 v[84:87], v[144:147], v[176:179], v[84:87]
	v_mfma_f32_16x16x32_bf16 v[80:83], v[152:155], v[176:179], v[80:83]
	v_mfma_f32_16x16x32_bf16 v[68:71], v[144:147], v[192:195], v[68:71]
	v_mfma_f32_16x16x32_bf16 v[64:67], v[152:155], v[192:195], v[64:67]
	v_mfma_f32_16x16x32_bf16 v[132:135], v[148:151], v[164:167], v[132:135]
	v_mfma_f32_16x16x32_bf16 v[128:131], v[156:159], v[164:167], v[128:131]
	v_mfma_f32_16x16x32_bf16 v[100:103], v[148:151], v[172:175], v[100:103]
	v_mfma_f32_16x16x32_bf16 v[96:99], v[156:159], v[172:175], v[96:99]
	v_mfma_f32_16x16x32_bf16 v[84:87], v[148:151], v[180:183], v[84:87]
	v_mfma_f32_16x16x32_bf16 v[80:83], v[156:159], v[180:183], v[80:83]
	v_mfma_f32_16x16x32_bf16 v[68:71], v[148:151], v[196:199], v[68:71]
	v_mfma_f32_16x16x32_bf16 v[64:67], v[156:159], v[196:199], v[64:67]
	s_barrier
	s_add_i32 s53, s56, s2
	v_lshl_add_u64 v[200:201], s[36:37], 0, v[186:187]
	s_mov_b32 m0, s53
	ds_read_b128 v[160:163], v215 offset:16384
	ds_read_b128 v[164:167], v215 offset:17408
	ds_read_b128 v[168:171], v215 offset:18432
	ds_read_b128 v[172:175], v215 offset:19456
	ds_read_b128 v[176:179], v215 offset:20480
	ds_read_b128 v[180:183], v215 offset:21504
	ds_read_b128 v[192:195], v215 offset:22528
	ds_read_b128 v[196:199], v215 offset:23552
	global_load_lds_dwordx4 v[200:201], off
	s_add_i32 m0, s53, 0x2000
	s_add_u32 s54, s36, 0x208000
	v_lshl_add_u64 v[202:203], s[36:37], 0, v[190:191]
	s_addc_u32 s55, s37, 0
	s_add_i32 s53, s45, s2
	global_load_lds_dwordx4 v[202:203], off
	v_lshl_add_u64 v[204:205], s[54:55], 0, v[186:187]
	s_mov_b32 m0, s53
	s_nop 0
	global_load_lds_dwordx4 v[204:205], off
	v_lshl_add_u64 v[204:205], s[54:55], 0, v[190:191]
	s_add_i32 m0, s53, 0x2000
	s_nop 0
	global_load_lds_dwordx4 v[204:205], off
	v_lshl_add_u64 v[204:205], s[38:39], 0, v[184:185]
	s_mov_b32 m0, s3
	s_nop 0
	global_load_lds_dwordx4 v[204:205], off
	v_lshl_add_u64 v[204:205], s[38:39], 0, v[188:189]
	s_mov_b32 m0, s33
	s_nop 0
	global_load_lds_dwordx4 v[204:205], off
	s_waitcnt vmcnt(8)
	s_waitcnt lgkmcnt(0)
	s_barrier
	s_waitcnt lgkmcnt(0)
	v_mfma_f32_16x16x32_bf16 v[60:63], v[104:107], v[160:163], v[60:63]
	v_mfma_f32_16x16x32_bf16 v[56:59], v[120:123], v[160:163], v[56:59]
	v_mfma_f32_16x16x32_bf16 v[44:47], v[104:107], v[168:171], v[44:47]
	v_mfma_f32_16x16x32_bf16 v[40:43], v[120:123], v[168:171], v[40:43]
	v_mfma_f32_16x16x32_bf16 v[28:31], v[104:107], v[176:179], v[28:31]
	v_mfma_f32_16x16x32_bf16 v[24:27], v[120:123], v[176:179], v[24:27]
	v_mfma_f32_16x16x32_bf16 v[12:15], v[104:107], v[192:195], v[12:15]
	v_mfma_f32_16x16x32_bf16 v[8:11], v[120:123], v[192:195], v[8:11]
	v_mfma_f32_16x16x32_bf16 v[60:63], v[108:111], v[164:167], v[60:63]
	v_mfma_f32_16x16x32_bf16 v[56:59], v[124:127], v[164:167], v[56:59]
	v_mfma_f32_16x16x32_bf16 v[44:47], v[108:111], v[172:175], v[44:47]
	v_mfma_f32_16x16x32_bf16 v[40:43], v[124:127], v[172:175], v[40:43]
	v_mfma_f32_16x16x32_bf16 v[28:31], v[108:111], v[180:183], v[28:31]
	v_mfma_f32_16x16x32_bf16 v[24:27], v[124:127], v[180:183], v[24:27]
	v_mfma_f32_16x16x32_bf16 v[12:15], v[108:111], v[196:199], v[12:15]
	v_mfma_f32_16x16x32_bf16 v[8:11], v[124:127], v[196:199], v[8:11]
	v_mfma_f32_16x16x32_bf16 v[52:55], v[144:147], v[160:163], v[52:55]
	v_mfma_f32_16x16x32_bf16 v[48:51], v[152:155], v[160:163], v[48:51]
	v_mfma_f32_16x16x32_bf16 v[36:39], v[144:147], v[168:171], v[36:39]
	v_mfma_f32_16x16x32_bf16 v[32:35], v[152:155], v[168:171], v[32:35]
	v_mfma_f32_16x16x32_bf16 v[20:23], v[144:147], v[176:179], v[20:23]
	v_mfma_f32_16x16x32_bf16 v[16:19], v[152:155], v[176:179], v[16:19]
	v_mfma_f32_16x16x32_bf16 v[4:7], v[144:147], v[192:195], v[4:7]
	v_mfma_f32_16x16x32_bf16 v[0:3], v[152:155], v[192:195], v[0:3]
	v_mfma_f32_16x16x32_bf16 v[52:55], v[148:151], v[164:167], v[52:55]
	v_mfma_f32_16x16x32_bf16 v[48:51], v[156:159], v[164:167], v[48:51]
	v_mfma_f32_16x16x32_bf16 v[36:39], v[148:151], v[172:175], v[36:39]
	v_mfma_f32_16x16x32_bf16 v[32:35], v[156:159], v[172:175], v[32:35]
	v_mfma_f32_16x16x32_bf16 v[20:23], v[148:151], v[180:183], v[20:23]
	v_mfma_f32_16x16x32_bf16 v[16:19], v[156:159], v[180:183], v[16:19]
	v_mfma_f32_16x16x32_bf16 v[4:7], v[148:151], v[196:199], v[4:7]
	v_mfma_f32_16x16x32_bf16 v[0:3], v[156:159], v[196:199], v[0:3]
	s_barrier
	s_add_i32 s53, 0, 0x18000
	s_add_i32 s54, 0, 0x1c000
	v_add_u32_e32 v124, s53, v211
	v_add_u32_e32 v156, s54, v211
	ds_read_b128 v[104:107], v124
	ds_read_b128 v[108:111], v124 offset:1024
	ds_read_b128 v[120:123], v124 offset:2048
	ds_read_b128 v[124:127], v124 offset:3072
	ds_read_b128 v[144:147], v156
	ds_read_b128 v[148:151], v156 offset:1024
	ds_read_b128 v[152:155], v156 offset:2048
	ds_read_b128 v[156:159], v156 offset:3072
	s_add_u32 s38, s38, 0x10000
	s_addc_u32 s39, s39, 0
	s_mov_b32 m0, s40
	v_lshl_add_u64 v[204:205], s[38:39], 0, v[184:185]
	ds_read_b128 v[160:163], v215 offset:32768
	ds_read_b128 v[164:167], v215 offset:33792
	ds_read_b128 v[168:171], v215 offset:34816
	ds_read_b128 v[172:175], v215 offset:35840
	ds_read_b128 v[176:179], v215 offset:36864
	ds_read_b128 v[180:183], v215 offset:37888
	ds_read_b128 v[192:195], v215 offset:38912
	ds_read_b128 v[196:199], v215 offset:39936
	global_load_lds_dwordx4 v[204:205], off
	v_lshl_add_u64 v[204:205], s[38:39], 0, v[188:189]
	s_mov_b32 m0, s41
	s_nop 0
	global_load_lds_dwordx4 v[204:205], off
	s_waitcnt vmcnt(8)
	s_waitcnt lgkmcnt(0)
	s_barrier
	s_waitcnt lgkmcnt(0)
	v_mfma_f32_16x16x32_bf16 v[140:143], v[104:107], v[160:163], v[140:143]
	v_mfma_f32_16x16x32_bf16 v[136:139], v[120:123], v[160:163], v[136:139]
	v_mfma_f32_16x16x32_bf16 v[116:119], v[104:107], v[168:171], v[116:119]
	v_mfma_f32_16x16x32_bf16 v[112:115], v[120:123], v[168:171], v[112:115]
	v_mfma_f32_16x16x32_bf16 v[92:95], v[104:107], v[176:179], v[92:95]
	v_mfma_f32_16x16x32_bf16 v[88:91], v[120:123], v[176:179], v[88:91]
	v_mfma_f32_16x16x32_bf16 v[76:79], v[104:107], v[192:195], v[76:79]
	v_mfma_f32_16x16x32_bf16 v[72:75], v[120:123], v[192:195], v[72:75]
	v_mfma_f32_16x16x32_bf16 v[140:143], v[108:111], v[164:167], v[140:143]
	v_mfma_f32_16x16x32_bf16 v[136:139], v[124:127], v[164:167], v[136:139]
	v_mfma_f32_16x16x32_bf16 v[116:119], v[108:111], v[172:175], v[116:119]
	v_mfma_f32_16x16x32_bf16 v[112:115], v[124:127], v[172:175], v[112:115]
	v_mfma_f32_16x16x32_bf16 v[92:95], v[108:111], v[180:183], v[92:95]
	v_mfma_f32_16x16x32_bf16 v[88:91], v[124:127], v[180:183], v[88:91]
	v_mfma_f32_16x16x32_bf16 v[76:79], v[108:111], v[196:199], v[76:79]
	v_mfma_f32_16x16x32_bf16 v[72:75], v[124:127], v[196:199], v[72:75]
	v_mfma_f32_16x16x32_bf16 v[132:135], v[144:147], v[160:163], v[132:135]
	v_mfma_f32_16x16x32_bf16 v[128:131], v[152:155], v[160:163], v[128:131]
	v_mfma_f32_16x16x32_bf16 v[100:103], v[144:147], v[168:171], v[100:103]
	v_mfma_f32_16x16x32_bf16 v[96:99], v[152:155], v[168:171], v[96:99]
	v_mfma_f32_16x16x32_bf16 v[84:87], v[144:147], v[176:179], v[84:87]
	v_mfma_f32_16x16x32_bf16 v[80:83], v[152:155], v[176:179], v[80:83]
	v_mfma_f32_16x16x32_bf16 v[68:71], v[144:147], v[192:195], v[68:71]
	v_mfma_f32_16x16x32_bf16 v[64:67], v[152:155], v[192:195], v[64:67]
	v_mfma_f32_16x16x32_bf16 v[132:135], v[148:151], v[164:167], v[132:135]
	v_mfma_f32_16x16x32_bf16 v[128:131], v[156:159], v[164:167], v[128:131]
	v_mfma_f32_16x16x32_bf16 v[100:103], v[148:151], v[172:175], v[100:103]
	v_mfma_f32_16x16x32_bf16 v[96:99], v[156:159], v[172:175], v[96:99]
	v_mfma_f32_16x16x32_bf16 v[84:87], v[148:151], v[180:183], v[84:87]
	v_mfma_f32_16x16x32_bf16 v[80:83], v[156:159], v[180:183], v[80:83]
	v_mfma_f32_16x16x32_bf16 v[68:71], v[148:151], v[196:199], v[68:71]
	v_mfma_f32_16x16x32_bf16 v[64:67], v[156:159], v[196:199], v[64:67]
	s_barrier
	s_add_i32 s38, s53, s2
	v_lshl_add_u64 v[200:201], v[200:201], 0, s[16:17]
	s_mov_b32 m0, s38
	ds_read_b128 v[160:163], v215 offset:49152
	ds_read_b128 v[164:167], v215 offset:50176
	ds_read_b128 v[168:171], v215 offset:51200
	ds_read_b128 v[172:175], v215 offset:52224
	ds_read_b128 v[176:179], v215 offset:53248
	ds_read_b128 v[180:183], v215 offset:54272
	ds_read_b128 v[192:195], v215 offset:55296
	ds_read_b128 v[196:199], v215 offset:56320
	global_load_lds_dwordx4 v[200:201], off
	s_add_i32 m0, s38, 0x2000
	s_add_u32 s36, s36, 0x208080
	v_lshl_add_u64 v[200:201], v[202:203], 0, s[16:17]
	s_addc_u32 s37, s37, 0
	s_add_i32 s38, s54, s2
	global_load_lds_dwordx4 v[200:201], off
	v_lshl_add_u64 v[200:201], s[36:37], 0, v[186:187]
	s_mov_b32 m0, s38
	s_nop 0
	global_load_lds_dwordx4 v[200:201], off
	v_lshl_add_u64 v[200:201], s[36:37], 0, v[190:191]
	s_add_i32 m0, s38, 0x2000
	s_nop 0
	global_load_lds_dwordx4 v[200:201], off
	v_lshl_add_u64 v[200:201], s[30:31], 0, v[184:185]
	s_mov_b32 m0, s43
	s_nop 0
	global_load_lds_dwordx4 v[200:201], off
	v_lshl_add_u64 v[200:201], s[30:31], 0, v[188:189]
	s_mov_b32 m0, s44
	s_nop 0
	global_load_lds_dwordx4 v[200:201], off
	s_waitcnt vmcnt(8)
	s_waitcnt lgkmcnt(0)
	s_barrier
	s_waitcnt lgkmcnt(0)
	v_mfma_f32_16x16x32_bf16 v[60:63], v[104:107], v[160:163], v[60:63]
	v_mfma_f32_16x16x32_bf16 v[56:59], v[120:123], v[160:163], v[56:59]
	v_mfma_f32_16x16x32_bf16 v[44:47], v[104:107], v[168:171], v[44:47]
	v_mfma_f32_16x16x32_bf16 v[40:43], v[120:123], v[168:171], v[40:43]
	v_mfma_f32_16x16x32_bf16 v[28:31], v[104:107], v[176:179], v[28:31]
	v_mfma_f32_16x16x32_bf16 v[24:27], v[120:123], v[176:179], v[24:27]
	v_mfma_f32_16x16x32_bf16 v[12:15], v[104:107], v[192:195], v[12:15]
	v_mfma_f32_16x16x32_bf16 v[8:11], v[120:123], v[192:195], v[8:11]
	v_mfma_f32_16x16x32_bf16 v[60:63], v[108:111], v[164:167], v[60:63]
	v_mfma_f32_16x16x32_bf16 v[56:59], v[124:127], v[164:167], v[56:59]
	v_mfma_f32_16x16x32_bf16 v[44:47], v[108:111], v[172:175], v[44:47]
	v_mfma_f32_16x16x32_bf16 v[40:43], v[124:127], v[172:175], v[40:43]
	v_mfma_f32_16x16x32_bf16 v[28:31], v[108:111], v[180:183], v[28:31]
	v_mfma_f32_16x16x32_bf16 v[24:27], v[124:127], v[180:183], v[24:27]
	v_mfma_f32_16x16x32_bf16 v[12:15], v[108:111], v[196:199], v[12:15]
	v_mfma_f32_16x16x32_bf16 v[8:11], v[124:127], v[196:199], v[8:11]
	v_mfma_f32_16x16x32_bf16 v[52:55], v[144:147], v[160:163], v[52:55]
	v_mfma_f32_16x16x32_bf16 v[48:51], v[152:155], v[160:163], v[48:51]
	v_mfma_f32_16x16x32_bf16 v[36:39], v[144:147], v[168:171], v[36:39]
	v_mfma_f32_16x16x32_bf16 v[32:35], v[152:155], v[168:171], v[32:35]
	v_mfma_f32_16x16x32_bf16 v[20:23], v[144:147], v[176:179], v[20:23]
	v_mfma_f32_16x16x32_bf16 v[16:19], v[152:155], v[176:179], v[16:19]
	v_mfma_f32_16x16x32_bf16 v[4:7], v[144:147], v[192:195], v[4:7]
	v_mfma_f32_16x16x32_bf16 v[0:3], v[152:155], v[192:195], v[0:3]
	v_mfma_f32_16x16x32_bf16 v[52:55], v[148:151], v[164:167], v[52:55]
	v_mfma_f32_16x16x32_bf16 v[48:51], v[156:159], v[164:167], v[48:51]
	v_mfma_f32_16x16x32_bf16 v[36:39], v[148:151], v[172:175], v[36:39]
	v_mfma_f32_16x16x32_bf16 v[32:35], v[156:159], v[172:175], v[32:35]
	v_mfma_f32_16x16x32_bf16 v[20:23], v[148:151], v[180:183], v[20:23]
	v_mfma_f32_16x16x32_bf16 v[16:19], v[156:159], v[180:183], v[16:19]
	v_mfma_f32_16x16x32_bf16 v[4:7], v[148:151], v[196:199], v[4:7]
	v_mfma_f32_16x16x32_bf16 v[0:3], v[156:159], v[196:199], v[0:3]
	s_barrier
	s_add_i32 s51, s51, 2
	s_add_i32 s52, s52, 0x10000
	s_cmpk_gt_u32 s51, 0x7d
	s_mov_b64 s[30:31], s[34:35]
	s_cbranch_scc0 .LBB0_844
	s_and_b64 vcc, exec, s[18:19]
	s_cbranch_vccz .LBB0_847
	s_barrier
